# scan4 + stagger + rope-table loads in phase 1/18 epilogues pipelined one iteration ahead (hipcc hazard spacing kept)
# baseline (speedup 1.0000x reference)
; __device__ __forceinline__ u32x4 pack8(const f32x4 a, const f32x4 b) { u32x4 w; w.x = cvt_pk_bf16(a[0], a[1]); w.y = cvt_pk_bf16(a[2], a[3]); w.z = cvt_pk_bf16(b[0], b[1]); w.w = cvt_pk_bf16(b[2], b[3]); return w; }
; __device__ __forceinline__ void rope8(const float* tab64, int row, int fq, const f32x4 x1a, const f32x4 x2a, const f32x4 x1b, const f32x4 x2b, f32x4& a1, f32x4& a2, f32x4& b1, f32x4& b2) {
;     const float* tp = tab64 + ((size_t)pos_index_(row) * 32 + 8 * fq) * 2;
;     const f32x4 c0 = *(const f32x4*)tp, c1 = *(const f32x4*)(tp + 4), c2 = *(const f32x4*)(tp + 8), c3 = *(const f32x4*)(tp + 12);
;     rope4(x1a, x2a, c0, c1, a1, a2); rope4(x1b, x2b, c2, c3, b1, b2);
;     __device__ __forceinline__ void operator()(const f32x4 (&acc)[2][2][4][2], const Unit& u, int wr, int wc, int fr, int fq) const {
;     ...
;             for (int m = 0; m < 4; ++m) {
;                 const int rowb = u.pm * BM + ai * HALF + wr * 64 + m * 16, row0 = rowb + (fr & 7); const size_t ro0 = (size_t)row0 * 2048;
;                 float* f0 = row0 < 8192 ? (type == 1 ? okp : ovp) + ro0 : (type == 1 ? oks : ovs) + (ro0 - (size_t)8192 * 2048);
;                 if (type < 2) {
;                     f32x4 a1, a2, b1, b2; rope8(tab64, rowb + fr, fq, acc[ai][0][m][0], acc[ai][1][m][0], acc[ai][0][m][1], acc[ai][1][m][1], a1, a2, b1, b2);
;                     if (type == 0) { a1 = a1 * qscale; a2 = a2 * qscale; b1 = b1 * qscale; b2 = b2 * qscale; }
;                     st2_bf16((type == 0 ? QA : KA) + ro0 + cw + (lo ? 0 : 32), 8 * 2048, pack8(a1, b1), pack8(a2, b2), lo, dry);
;                     if (type == 1) { st2_f32<true>(f0 + cw + (lo ? 0 : 4), 8 * 2048, a1, b1, lo, dry); st2_f32<true>(f0 + cw + 32 + (lo ? 0 : 4), 8 * 2048, a2, b2, lo, dry); }
.LBB0_192:
	v_cndmask_b32_e64 v130, 0, 1, s[6:7]
	s_andn2_b64 vcc, exec, s[10:11]
	v_lshlrev_b32_e32 v168, 2, v154
	v_cmp_ne_u32_e64 s[6:7], 1, v130
	s_cbranch_vccnz .LBB0_197
	v_or_b32_e32 v130, s31, v141
	v_bitop3_b32 v131, s31, v161, v141 bitop3:0xc8
	v_cmp_gt_i32_e32 vcc, s49, v130
	v_readlane_b32 s10, v254, 22
	v_readlane_b32 s11, v254, 23
	v_cndmask_b32_e32 v130, v155, v131, vcc
	v_lshl_or_b32 v130, v130, 8, v168
	s_nop 2
	global_load_dwordx4 v[170:173], v130, s[10:11]
	global_load_dwordx4 v[174:177], v130, s[10:11] offset:16
	global_load_dwordx4 v[178:181], v130, s[10:11] offset:32
	global_load_dwordx4 v[182:185], v130, s[10:11] offset:48
	s_add_i32 s98, s35, s66
	v_or_b32_e32 v252, s98, v141
	v_bitop3_b32 v253, s98, v162, v141 bitop3:0xc8
	v_and_or_b32 v236, v252, 31, v163
	v_cmp_gt_i32_e32 vcc, s49, v252
	v_readlane_b32 s100, v254, 22
	v_readlane_b32 s101, v254, 23
	v_cndmask_b32_e32 v252, v236, v253, vcc
	v_lshl_or_b32 v252, v252, 8, v168
	s_nop 2
	global_load_dwordx4 v[236:239], v252, s[100:101]
	global_load_dwordx4 v[240:243], v252, s[100:101] offset:16
	global_load_dwordx4 v[244:247], v252, s[100:101] offset:32
	global_load_dwordx4 v[248:251], v252, s[100:101] offset:48
	s_load_dwordx4 s[72:75], s[88:89], 0xe8
	s_and_b64 vcc, exec, s[6:7]
	s_mov_b64 s[10:11], 0x1b500000
	s_waitcnt vmcnt(4)
	v_mov_b32_e32 v130, v170
	v_mul_f32_e32 v170, v128, v174
	v_mul_f32_e32 v186, v120, v175
	v_mul_f32_e32 v174, v120, v174
	v_mul_f32_e32 v188, v128, v175
	v_mov_b32_e32 v120, v129
	v_mov_b32_e32 v128, v121
	v_mov_b32_e32 v190, v178
	v_mul_f32_e32 v178, v124, v182
	v_mul_f32_e32 v192, v116, v183
	v_mul_f32_e32 v182, v116, v182
	v_mul_f32_e32 v194, v124, v183
	v_mov_b32_e32 v116, v125
	v_mov_b32_e32 v124, v117
	v_mov_b32_e32 v131, v172
	v_mov_b32_e32 v172, v171
	v_mov_b32_e32 v191, v180
	v_mov_b32_e32 v180, v179
	v_pk_mul_f32 v[120:121], v[120:121], v[176:177]
	v_pk_mul_f32 v[128:129], v[128:129], v[176:177]
	v_pk_mul_f32 v[198:199], v[116:117], v[184:185]
	v_pk_mul_f32 v[184:185], v[124:125], v[184:185]
	v_pk_mul_f32 v[196:197], v[118:119], v[172:173]
	v_pk_mul_f32 v[172:173], v[126:127], v[172:173]
	v_pk_mul_f32 v[176:177], v[114:115], v[180:181]
	v_pk_mul_f32 v[180:181], v[122:123], v[180:181]
	v_mov_b32_e32 v171, v120
	v_mov_b32_e32 v187, v121
	v_mov_b32_e32 v175, v128
	v_mov_b32_e32 v189, v129
	v_mov_b32_e32 v179, v198
	v_mov_b32_e32 v193, v199
	v_mov_b32_e32 v183, v184
	v_mov_b32_e32 v195, v185
	v_pk_fma_f32 v[124:125], v[126:127], v[130:131], v[196:197] neg_lo:[0,0,1] neg_hi:[0,0,1]
	v_pk_fma_f32 v[116:117], v[118:119], v[130:131], v[172:173]
	v_pk_fma_f32 v[128:129], v[122:123], v[190:191], v[176:177] neg_lo:[0,0,1] neg_hi:[0,0,1]
	v_pk_fma_f32 v[120:121], v[114:115], v[190:191], v[180:181]
	v_pk_add_f32 v[126:127], v[170:171], v[186:187] neg_lo:[0,1] neg_hi:[0,1]
	v_pk_add_f32 v[118:119], v[174:175], v[188:189]
	v_pk_add_f32 v[130:131], v[178:179], v[192:193] neg_lo:[0,1] neg_hi:[0,1]
	v_pk_add_f32 v[122:123], v[182:183], v[194:195]
	s_cbranch_vccnz .LBB0_195
	v_pk_mul_f32 v[126:127], v[126:127], s[28:29] op_sel_hi:[1,0]
	v_pk_mul_f32 v[124:125], v[124:125], s[28:29] op_sel_hi:[1,0]
	v_pk_mul_f32 v[118:119], v[118:119], s[28:29] op_sel_hi:[1,0]
	v_pk_mul_f32 v[116:117], v[116:117], s[28:29] op_sel_hi:[1,0]
	v_pk_mul_f32 v[130:131], v[130:131], s[28:29] op_sel_hi:[1,0]
	v_pk_mul_f32 v[128:129], v[128:129], s[28:29] op_sel_hi:[1,0]
	v_pk_mul_f32 v[122:123], v[122:123], s[28:29] op_sel_hi:[1,0]
	v_pk_mul_f32 v[120:121], v[120:121], s[28:29] op_sel_hi:[1,0]
	s_mov_b64 s[10:11], 0x19300000

; __device__ __forceinline__ u32x4 pack8(const f32x4 a, const f32x4 b) { u32x4 w; w.x = cvt_pk_bf16(a[0], a[1]); w.y = cvt_pk_bf16(a[2], a[3]); w.z = cvt_pk_bf16(b[0], b[1]); w.w = cvt_pk_bf16(b[2], b[3]); return w; }
; __device__ __forceinline__ void rope8(const float* tab64, int row, int fq, const f32x4 x1a, const f32x4 x2a, const f32x4 x1b, const f32x4 x2b, f32x4& a1, f32x4& a2, f32x4& b1, f32x4& b2) {
;     const float* tp = tab64 + ((size_t)pos_index_(row) * 32 + 8 * fq) * 2;
;     const f32x4 c0 = *(const f32x4*)tp, c1 = *(const f32x4*)(tp + 4), c2 = *(const f32x4*)(tp + 8), c3 = *(const f32x4*)(tp + 12);
;     rope4(x1a, x2a, c0, c1, a1, a2); rope4(x1b, x2b, c2, c3, b1, b2);
;     __device__ __forceinline__ void operator()(const f32x4 (&acc)[2][2][4][2], const Unit& u, int wr, int wc, int fr, int fq) const {
;     ...
;             for (int m = 0; m < 4; ++m) {
;                 const int rowb = u.pm * BM + ai * HALF + wr * 64 + m * 16, row0 = rowb + (fr & 7); const size_t ro0 = (size_t)row0 * 2048;
;                 float* f0 = row0 < 8192 ? (type == 1 ? okp : ovp) + ro0 : (type == 1 ? oks : ovs) + (ro0 - (size_t)8192 * 2048);
;                 if (type < 2) {
;                     f32x4 a1, a2, b1, b2; rope8(tab64, rowb + fr, fq, acc[ai][0][m][0], acc[ai][1][m][0], acc[ai][0][m][1], acc[ai][1][m][1], a1, a2, b1, b2);
;                     if (type == 0) { a1 = a1 * qscale; a2 = a2 * qscale; b1 = b1 * qscale; b2 = b2 * qscale; }
;                     st2_bf16((type == 0 ? QA : KA) + ro0 + cw + (lo ? 0 : 32), 8 * 2048, pack8(a1, b1), pack8(a2, b2), lo, dry);
;                     if (type == 1) { st2_f32<true>(f0 + cw + (lo ? 0 : 4), 8 * 2048, a1, b1, lo, dry); st2_f32<true>(f0 + cw + 32 + (lo ? 0 : 4), 8 * 2048, a2, b2, lo, dry); }
.Lrope_j_p1_1:
	v_mov_b64_e32 v[120:121], v[236:237]
	v_mov_b64_e32 v[122:123], v[238:239]
	v_mov_b64_e32 v[124:125], v[240:241]
	v_mov_b64_e32 v[126:127], v[242:243]
	v_mov_b64_e32 v[128:129], v[244:245]
	v_mov_b64_e32 v[130:131], v[246:247]
	v_mov_b64_e32 v[150:151], v[248:249]
	v_mov_b64_e32 v[152:153], v[250:251]
	s_add_i32 s98, s35, s67
	v_or_b32_e32 v252, s98, v141
	v_bitop3_b32 v253, s98, v165, v141 bitop3:0xc8
	v_and_or_b32 v236, v252, 47, v163
	v_cmp_gt_i32_e32 vcc, s49, v252
	v_readlane_b32 s100, v254, 22
	v_readlane_b32 s101, v254, 23
	v_cndmask_b32_e32 v252, v236, v253, vcc
	v_lshl_or_b32 v252, v252, 8, v168
	s_nop 2
	global_load_dwordx4 v[236:239], v252, s[100:101]
	global_load_dwordx4 v[240:243], v252, s[100:101] offset:16
	global_load_dwordx4 v[244:247], v252, s[100:101] offset:32
	global_load_dwordx4 v[248:251], v252, s[100:101] offset:48
	s_and_b64 vcc, exec, s[6:7]
	s_mov_b64 s[40:41], 0x1b500000
	v_mov_b32_e32 v114, v120
	v_mul_f32_e32 v120, v112, v124
	v_mul_f32_e32 v170, v104, v125
	v_mul_f32_e32 v124, v104, v124
	v_mul_f32_e32 v172, v112, v125
	v_mov_b32_e32 v104, v113
	v_mov_b32_e32 v112, v105
	v_mov_b32_e32 v174, v128
	v_mul_f32_e32 v128, v108, v150
	v_mul_f32_e32 v176, v100, v151
	v_mul_f32_e32 v150, v100, v150
	v_mul_f32_e32 v178, v108, v151
	v_mov_b32_e32 v100, v109
	v_mov_b32_e32 v108, v101
	v_mov_b32_e32 v115, v122
	v_mov_b32_e32 v122, v121
	v_mov_b32_e32 v175, v130
	v_mov_b32_e32 v130, v129
	v_pk_mul_f32 v[104:105], v[104:105], v[126:127]
	v_pk_mul_f32 v[112:113], v[112:113], v[126:127]
	v_pk_mul_f32 v[182:183], v[100:101], v[152:153]
	v_pk_mul_f32 v[152:153], v[108:109], v[152:153]
	v_pk_mul_f32 v[180:181], v[102:103], v[122:123]
	v_pk_mul_f32 v[122:123], v[110:111], v[122:123]
	v_pk_mul_f32 v[126:127], v[98:99], v[130:131]
	v_pk_mul_f32 v[130:131], v[106:107], v[130:131]
	v_mov_b32_e32 v121, v104
	v_mov_b32_e32 v171, v105
	v_mov_b32_e32 v125, v112
	v_mov_b32_e32 v173, v113
	v_mov_b32_e32 v129, v182
	v_mov_b32_e32 v177, v183
	v_mov_b32_e32 v151, v152
	v_mov_b32_e32 v179, v153
	v_pk_fma_f32 v[108:109], v[110:111], v[114:115], v[180:181] neg_lo:[0,0,1] neg_hi:[0,0,1]
	v_pk_fma_f32 v[100:101], v[102:103], v[114:115], v[122:123]
	v_pk_fma_f32 v[112:113], v[106:107], v[174:175], v[126:127] neg_lo:[0,0,1] neg_hi:[0,0,1]
	v_pk_fma_f32 v[104:105], v[98:99], v[174:175], v[130:131]
	v_pk_add_f32 v[110:111], v[120:121], v[170:171] neg_lo:[0,1] neg_hi:[0,1]
	v_pk_add_f32 v[102:103], v[124:125], v[172:173]
	v_pk_add_f32 v[114:115], v[128:129], v[176:177] neg_lo:[0,1] neg_hi:[0,1]
	v_pk_add_f32 v[106:107], v[150:151], v[178:179]
	s_cbranch_vccnz .LBB0_210
	v_pk_mul_f32 v[110:111], v[110:111], s[28:29] op_sel_hi:[1,0]
	v_pk_mul_f32 v[108:109], v[108:109], s[28:29] op_sel_hi:[1,0]
	v_pk_mul_f32 v[102:103], v[102:103], s[28:29] op_sel_hi:[1,0]
	v_pk_mul_f32 v[100:101], v[100:101], s[28:29] op_sel_hi:[1,0]
	v_pk_mul_f32 v[114:115], v[114:115], s[28:29] op_sel_hi:[1,0]
	v_pk_mul_f32 v[112:113], v[112:113], s[28:29] op_sel_hi:[1,0]
	v_pk_mul_f32 v[106:107], v[106:107], s[28:29] op_sel_hi:[1,0]
	v_pk_mul_f32 v[104:105], v[104:105], s[28:29] op_sel_hi:[1,0]
	s_mov_b64 s[40:41], 0x19300000

; __device__ __forceinline__ u32x4 pack8(const f32x4 a, const f32x4 b) { u32x4 w; w.x = cvt_pk_bf16(a[0], a[1]); w.y = cvt_pk_bf16(a[2], a[3]); w.z = cvt_pk_bf16(b[0], b[1]); w.w = cvt_pk_bf16(b[2], b[3]); return w; }
; __device__ __forceinline__ void rope8(const float* tab64, int row, int fq, const f32x4 x1a, const f32x4 x2a, const f32x4 x1b, const f32x4 x2b, f32x4& a1, f32x4& a2, f32x4& b1, f32x4& b2) {
;     const float* tp = tab64 + ((size_t)pos_index_(row) * 32 + 8 * fq) * 2;
;     const f32x4 c0 = *(const f32x4*)tp, c1 = *(const f32x4*)(tp + 4), c2 = *(const f32x4*)(tp + 8), c3 = *(const f32x4*)(tp + 12);
;     rope4(x1a, x2a, c0, c1, a1, a2); rope4(x1b, x2b, c2, c3, b1, b2);
;     __device__ __forceinline__ void operator()(const f32x4 (&acc)[2][2][4][2], const Unit& u, int wr, int wc, int fr, int fq) const {
;     ...
;             for (int m = 0; m < 4; ++m) {
;                 const int rowb = u.pm * BM + ai * HALF + wr * 64 + m * 16, row0 = rowb + (fr & 7); const size_t ro0 = (size_t)row0 * 2048;
;                 float* f0 = row0 < 8192 ? (type == 1 ? okp : ovp) + ro0 : (type == 1 ? oks : ovs) + (ro0 - (size_t)8192 * 2048);
;                 if (type < 2) {
;                     f32x4 a1, a2, b1, b2; rope8(tab64, rowb + fr, fq, acc[ai][0][m][0], acc[ai][1][m][0], acc[ai][0][m][1], acc[ai][1][m][1], a1, a2, b1, b2);
;                     if (type == 0) { a1 = a1 * qscale; a2 = a2 * qscale; b1 = b1 * qscale; b2 = b2 * qscale; }
;                     st2_bf16((type == 0 ? QA : KA) + ro0 + cw + (lo ? 0 : 32), 8 * 2048, pack8(a1, b1), pack8(a2, b2), lo, dry);
;                     if (type == 1) { st2_f32<true>(f0 + cw + (lo ? 0 : 4), 8 * 2048, a1, b1, lo, dry); st2_f32<true>(f0 + cw + 32 + (lo ? 0 : 4), 8 * 2048, a2, b2, lo, dry); }
.Lrope_j_p1_2:
	v_mov_b64_e32 v[104:105], v[236:237]
	v_mov_b64_e32 v[106:107], v[238:239]
	v_mov_b64_e32 v[108:109], v[240:241]
	v_mov_b64_e32 v[110:111], v[242:243]
	v_mov_b64_e32 v[112:113], v[244:245]
	v_mov_b64_e32 v[114:115], v[246:247]
	v_mov_b64_e32 v[116:117], v[248:249]
	v_mov_b64_e32 v[118:119], v[250:251]
	s_add_i32 s98, s35, s68
	v_or_b32_e32 v252, s98, v141
	v_bitop3_b32 v253, s98, v166, v141 bitop3:0xc8
	v_and_or_b32 v236, v252, 63, v163
	v_cmp_gt_i32_e32 vcc, s49, v252
	v_readlane_b32 s100, v254, 22
	v_readlane_b32 s101, v254, 23
	v_cndmask_b32_e32 v252, v236, v253, vcc
	v_lshl_or_b32 v252, v252, 8, v168
	s_nop 2
	global_load_dwordx4 v[236:239], v252, s[100:101]
	global_load_dwordx4 v[240:243], v252, s[100:101] offset:16
	global_load_dwordx4 v[244:247], v252, s[100:101] offset:32
	global_load_dwordx4 v[248:251], v252, s[100:101] offset:48
	s_and_b64 vcc, exec, s[6:7]
	s_mov_b64 s[40:41], 0x1b500000
	v_mov_b32_e32 v98, v104
	v_mul_f32_e32 v104, v96, v108
	v_mul_f32_e32 v120, v88, v109
	v_mul_f32_e32 v108, v88, v108
	v_mul_f32_e32 v122, v96, v109
	v_mov_b32_e32 v88, v97
	v_mov_b32_e32 v96, v89
	v_mov_b32_e32 v124, v112
	v_mul_f32_e32 v112, v92, v116
	v_mul_f32_e32 v126, v84, v117
	v_mul_f32_e32 v116, v84, v116
	v_mul_f32_e32 v128, v92, v117
	v_mov_b32_e32 v84, v93
	v_mov_b32_e32 v92, v85
	v_mov_b32_e32 v99, v106
	v_mov_b32_e32 v106, v105
	v_mov_b32_e32 v125, v114
	v_mov_b32_e32 v114, v113
	v_pk_mul_f32 v[88:89], v[88:89], v[110:111]
	v_pk_mul_f32 v[96:97], v[96:97], v[110:111]
	v_pk_mul_f32 v[150:151], v[84:85], v[118:119]
	v_pk_mul_f32 v[118:119], v[92:93], v[118:119]
	v_pk_mul_f32 v[130:131], v[86:87], v[106:107]
	v_pk_mul_f32 v[106:107], v[94:95], v[106:107]
	v_pk_mul_f32 v[110:111], v[82:83], v[114:115]
	v_pk_mul_f32 v[114:115], v[90:91], v[114:115]
	v_mov_b32_e32 v105, v88
	v_mov_b32_e32 v121, v89
	v_mov_b32_e32 v109, v96
	v_mov_b32_e32 v123, v97
	v_mov_b32_e32 v113, v150
	v_mov_b32_e32 v127, v151
	v_mov_b32_e32 v117, v118
	v_mov_b32_e32 v129, v119
	v_pk_fma_f32 v[92:93], v[94:95], v[98:99], v[130:131] neg_lo:[0,0,1] neg_hi:[0,0,1]
	v_pk_fma_f32 v[84:85], v[86:87], v[98:99], v[106:107]
	v_pk_fma_f32 v[96:97], v[90:91], v[124:125], v[110:111] neg_lo:[0,0,1] neg_hi:[0,0,1]
	v_pk_fma_f32 v[88:89], v[82:83], v[124:125], v[114:115]
	v_pk_add_f32 v[94:95], v[104:105], v[120:121] neg_lo:[0,1] neg_hi:[0,1]
	v_pk_add_f32 v[86:87], v[108:109], v[122:123]
	v_pk_add_f32 v[98:99], v[112:113], v[126:127] neg_lo:[0,1] neg_hi:[0,1]
	v_pk_add_f32 v[90:91], v[116:117], v[128:129]
	s_cbranch_vccnz .LBB0_225
	v_pk_mul_f32 v[94:95], v[94:95], s[28:29] op_sel_hi:[1,0]
	v_pk_mul_f32 v[92:93], v[92:93], s[28:29] op_sel_hi:[1,0]
	v_pk_mul_f32 v[86:87], v[86:87], s[28:29] op_sel_hi:[1,0]
	v_pk_mul_f32 v[84:85], v[84:85], s[28:29] op_sel_hi:[1,0]
	v_pk_mul_f32 v[98:99], v[98:99], s[28:29] op_sel_hi:[1,0]
	v_pk_mul_f32 v[96:97], v[96:97], s[28:29] op_sel_hi:[1,0]
	v_pk_mul_f32 v[90:91], v[90:91], s[28:29] op_sel_hi:[1,0]
	v_pk_mul_f32 v[88:89], v[88:89], s[28:29] op_sel_hi:[1,0]
	s_mov_b64 s[40:41], 0x19300000

; __device__ __forceinline__ u32x4 pack8(const f32x4 a, const f32x4 b) { u32x4 w; w.x = cvt_pk_bf16(a[0], a[1]); w.y = cvt_pk_bf16(a[2], a[3]); w.z = cvt_pk_bf16(b[0], b[1]); w.w = cvt_pk_bf16(b[2], b[3]); return w; }
; __device__ __forceinline__ void rope8(const float* tab64, int row, int fq, const f32x4 x1a, const f32x4 x2a, const f32x4 x1b, const f32x4 x2b, f32x4& a1, f32x4& a2, f32x4& b1, f32x4& b2) {
;     const float* tp = tab64 + ((size_t)pos_index_(row) * 32 + 8 * fq) * 2;
;     const f32x4 c0 = *(const f32x4*)tp, c1 = *(const f32x4*)(tp + 4), c2 = *(const f32x4*)(tp + 8), c3 = *(const f32x4*)(tp + 12);
;     rope4(x1a, x2a, c0, c1, a1, a2); rope4(x1b, x2b, c2, c3, b1, b2);
;     __device__ __forceinline__ void operator()(const f32x4 (&acc)[2][2][4][2], const Unit& u, int wr, int wc, int fr, int fq) const {
;     ...
;             for (int m = 0; m < 4; ++m) {
;                 const int rowb = u.pm * BM + ai * HALF + wr * 64 + m * 16, row0 = rowb + (fr & 7); const size_t ro0 = (size_t)row0 * 2048;
;                 float* f0 = row0 < 8192 ? (type == 1 ? okp : ovp) + ro0 : (type == 1 ? oks : ovs) + (ro0 - (size_t)8192 * 2048);
;                 if (type < 2) {
;                     f32x4 a1, a2, b1, b2; rope8(tab64, rowb + fr, fq, acc[ai][0][m][0], acc[ai][1][m][0], acc[ai][0][m][1], acc[ai][1][m][1], a1, a2, b1, b2);
;                     if (type == 0) { a1 = a1 * qscale; a2 = a2 * qscale; b1 = b1 * qscale; b2 = b2 * qscale; }
;                     st2_bf16((type == 0 ? QA : KA) + ro0 + cw + (lo ? 0 : 32), 8 * 2048, pack8(a1, b1), pack8(a2, b2), lo, dry);
;                     if (type == 1) { st2_f32<true>(f0 + cw + (lo ? 0 : 4), 8 * 2048, a1, b1, lo, dry); st2_f32<true>(f0 + cw + 32 + (lo ? 0 : 4), 8 * 2048, a2, b2, lo, dry); }
.Lrope_j_p1_3:
	v_mov_b64_e32 v[88:89], v[236:237]
	v_mov_b64_e32 v[90:91], v[238:239]
	v_mov_b64_e32 v[92:93], v[240:241]
	v_mov_b64_e32 v[94:95], v[242:243]
	v_mov_b64_e32 v[96:97], v[244:245]
	v_mov_b64_e32 v[98:99], v[246:247]
	v_mov_b64_e32 v[100:101], v[248:249]
	v_mov_b64_e32 v[102:103], v[250:251]
	s_add_i32 s98, s31, 0x80
	v_or_b32_e32 v252, s98, v141
	v_bitop3_b32 v253, s98, v161, v141 bitop3:0xc8
	v_cmp_gt_i32_e32 vcc, s49, v252
	v_readlane_b32 s100, v254, 22
	v_readlane_b32 s101, v254, 23
	v_cndmask_b32_e32 v252, v155, v253, vcc
	v_lshl_or_b32 v252, v252, 8, v168
	s_nop 2
	global_load_dwordx4 v[236:239], v252, s[100:101]
	global_load_dwordx4 v[240:243], v252, s[100:101] offset:16
	global_load_dwordx4 v[244:247], v252, s[100:101] offset:32
	global_load_dwordx4 v[248:251], v252, s[100:101] offset:48
	s_and_b64 vcc, exec, s[6:7]
	s_mov_b64 s[40:41], 0x1b500000
	v_mov_b32_e32 v82, v88
	v_mul_f32_e32 v88, v80, v92
	v_mul_f32_e32 v104, v72, v93
	v_mul_f32_e32 v92, v72, v92
	v_mul_f32_e32 v106, v80, v93
	v_mov_b32_e32 v72, v81
	v_mov_b32_e32 v80, v73
	v_mov_b32_e32 v108, v96
	v_mul_f32_e32 v96, v76, v100
	v_mul_f32_e32 v110, v68, v101
	v_mul_f32_e32 v100, v68, v100
	v_mul_f32_e32 v112, v76, v101
	v_mov_b32_e32 v68, v77
	v_mov_b32_e32 v76, v69
	v_mov_b32_e32 v83, v90
	v_mov_b32_e32 v90, v89
	v_mov_b32_e32 v109, v98
	v_mov_b32_e32 v98, v97
	v_pk_mul_f32 v[72:73], v[72:73], v[94:95]
	v_pk_mul_f32 v[80:81], v[80:81], v[94:95]
	v_pk_mul_f32 v[116:117], v[68:69], v[102:103]
	v_pk_mul_f32 v[102:103], v[76:77], v[102:103]
	v_pk_mul_f32 v[114:115], v[70:71], v[90:91]
	v_pk_mul_f32 v[90:91], v[78:79], v[90:91]
	v_pk_mul_f32 v[94:95], v[66:67], v[98:99]
	v_pk_mul_f32 v[98:99], v[74:75], v[98:99]
	v_mov_b32_e32 v89, v72
	v_mov_b32_e32 v105, v73
	v_mov_b32_e32 v93, v80
	v_mov_b32_e32 v107, v81
	v_mov_b32_e32 v97, v116
	v_mov_b32_e32 v111, v117
	v_mov_b32_e32 v101, v102
	v_mov_b32_e32 v113, v103
	v_pk_fma_f32 v[76:77], v[78:79], v[82:83], v[114:115] neg_lo:[0,0,1] neg_hi:[0,0,1]
	v_pk_fma_f32 v[68:69], v[70:71], v[82:83], v[90:91]
	v_pk_fma_f32 v[80:81], v[74:75], v[108:109], v[94:95] neg_lo:[0,0,1] neg_hi:[0,0,1]
	v_pk_fma_f32 v[72:73], v[66:67], v[108:109], v[98:99]
	v_pk_add_f32 v[78:79], v[88:89], v[104:105] neg_lo:[0,1] neg_hi:[0,1]
	v_pk_add_f32 v[70:71], v[92:93], v[106:107]
	v_pk_add_f32 v[82:83], v[96:97], v[110:111] neg_lo:[0,1] neg_hi:[0,1]
	v_pk_add_f32 v[74:75], v[100:101], v[112:113]
	s_cbranch_vccnz .LBB0_240
	v_pk_mul_f32 v[78:79], v[78:79], s[28:29] op_sel_hi:[1,0]
	v_pk_mul_f32 v[76:77], v[76:77], s[28:29] op_sel_hi:[1,0]
	v_pk_mul_f32 v[70:71], v[70:71], s[28:29] op_sel_hi:[1,0]
	v_pk_mul_f32 v[68:69], v[68:69], s[28:29] op_sel_hi:[1,0]
	v_pk_mul_f32 v[82:83], v[82:83], s[28:29] op_sel_hi:[1,0]
	v_pk_mul_f32 v[80:81], v[80:81], s[28:29] op_sel_hi:[1,0]
	v_pk_mul_f32 v[74:75], v[74:75], s[28:29] op_sel_hi:[1,0]
	v_pk_mul_f32 v[72:73], v[72:73], s[28:29] op_sel_hi:[1,0]
	s_mov_b64 s[40:41], 0x19300000

; __device__ __forceinline__ u32x4 pack8(const f32x4 a, const f32x4 b) { u32x4 w; w.x = cvt_pk_bf16(a[0], a[1]); w.y = cvt_pk_bf16(a[2], a[3]); w.z = cvt_pk_bf16(b[0], b[1]); w.w = cvt_pk_bf16(b[2], b[3]); return w; }
; __device__ __forceinline__ void rope8(const float* tab64, int row, int fq, const f32x4 x1a, const f32x4 x2a, const f32x4 x1b, const f32x4 x2b, f32x4& a1, f32x4& a2, f32x4& b1, f32x4& b2) {
;     const float* tp = tab64 + ((size_t)pos_index_(row) * 32 + 8 * fq) * 2;
;     const f32x4 c0 = *(const f32x4*)tp, c1 = *(const f32x4*)(tp + 4), c2 = *(const f32x4*)(tp + 8), c3 = *(const f32x4*)(tp + 12);
;     rope4(x1a, x2a, c0, c1, a1, a2); rope4(x1b, x2b, c2, c3, b1, b2);
; }
;     __device__ __forceinline__ void operator()(const f32x4 (&acc)[2][2][4][2], const Unit& u, int wr, int wc, int fr, int fq) const {
;         const int T = u.pn, type = T >> 3; const bool lo = fr < 8;
;         if (MK_EXPG && MK_EXPG != 6 && xskip) return; const bool dry = MK_EXPG == 6 && xskip;
;         const int cw = (T & 7) * 256 + 64 * wc + 8 * fq;
; #pragma unroll
;         for (int ai = 0; ai < 2; ++ai)
; #pragma unroll
;             for (int m = 0; m < 4; ++m) {
;                 const int rowb = u.pm * BM + ai * HALF + wr * 64 + m * 16, row0 = rowb + (fr & 7); const size_t ro0 = (size_t)row0 * 2048;
;                 float* f0 = row0 < 8192 ? (type == 1 ? okp : ovp) + ro0 : (type == 1 ? oks : ovs) + (ro0 - (size_t)8192 * 2048);
;                 if (type < 2) {
;                     f32x4 a1, a2, b1, b2; rope8(tab64, rowb + fr, fq, acc[ai][0][m][0], acc[ai][1][m][0], acc[ai][0][m][1], acc[ai][1][m][1], a1, a2, b1, b2);
;                     if (type == 0) { a1 = a1 * qscale; a2 = a2 * qscale; b1 = b1 * qscale; b2 = b2 * qscale; }
;                     st2_bf16((type == 0 ? QA : KA) + ro0 + cw + (lo ? 0 : 32), 8 * 2048, pack8(a1, b1), pack8(a2, b2), lo, dry);
;                     if (type == 1) { st2_f32<true>(f0 + cw + (lo ? 0 : 4), 8 * 2048, a1, b1, lo, dry); st2_f32<true>(f0 + cw + 32 + (lo ? 0 : 4), 8 * 2048, a2, b2, lo, dry); }
.Lrope_j_p1_4:
	v_mov_b64_e32 v[72:73], v[236:237]
	v_mov_b64_e32 v[74:75], v[238:239]
	v_mov_b64_e32 v[76:77], v[240:241]
	v_mov_b64_e32 v[78:79], v[242:243]
	v_mov_b64_e32 v[80:81], v[244:245]
	v_mov_b64_e32 v[82:83], v[246:247]
	v_mov_b64_e32 v[84:85], v[248:249]
	v_mov_b64_e32 v[86:87], v[250:251]
	s_add_i32 s98, s31, 0x90
	v_or_b32_e32 v252, s98, v141
	v_bitop3_b32 v253, s98, v162, v141 bitop3:0xc8
	v_and_or_b32 v236, v252, 31, v163
	v_cmp_gt_i32_e32 vcc, s49, v252
	v_readlane_b32 s100, v254, 22
	v_readlane_b32 s101, v254, 23
	v_cndmask_b32_e32 v252, v236, v253, vcc
	v_lshl_or_b32 v252, v252, 8, v168
	s_nop 2
	global_load_dwordx4 v[236:239], v252, s[100:101]
	global_load_dwordx4 v[240:243], v252, s[100:101] offset:16
	global_load_dwordx4 v[244:247], v252, s[100:101] offset:32
	global_load_dwordx4 v[248:251], v252, s[100:101] offset:48
	s_and_b64 vcc, exec, s[6:7]
	s_mov_b64 s[40:41], 0x1b500000
	v_mov_b32_e32 v66, v72
	v_mul_f32_e32 v72, v64, v76
	v_mul_f32_e32 v88, v56, v77
	v_mul_f32_e32 v76, v56, v76
	v_mul_f32_e32 v90, v64, v77
	v_mov_b32_e32 v56, v65
	v_mov_b32_e32 v64, v57
	v_mov_b32_e32 v92, v80
	v_mul_f32_e32 v80, v60, v84
	v_mul_f32_e32 v94, v52, v85
	v_mul_f32_e32 v84, v52, v84
	v_mul_f32_e32 v96, v60, v85
	v_mov_b32_e32 v52, v61
	v_mov_b32_e32 v60, v53
	v_mov_b32_e32 v67, v74
	v_mov_b32_e32 v74, v73
	v_mov_b32_e32 v93, v82
	v_mov_b32_e32 v82, v81
	v_pk_mul_f32 v[56:57], v[56:57], v[78:79]
	v_pk_mul_f32 v[64:65], v[64:65], v[78:79]
	v_pk_mul_f32 v[100:101], v[52:53], v[86:87]
	v_pk_mul_f32 v[86:87], v[60:61], v[86:87]
	v_pk_mul_f32 v[98:99], v[54:55], v[74:75]
	v_pk_mul_f32 v[74:75], v[62:63], v[74:75]
	v_pk_mul_f32 v[78:79], v[50:51], v[82:83]
	v_pk_mul_f32 v[82:83], v[58:59], v[82:83]
	v_mov_b32_e32 v73, v56
	v_mov_b32_e32 v89, v57
	v_mov_b32_e32 v77, v64
	v_mov_b32_e32 v91, v65
	v_mov_b32_e32 v81, v100
	v_mov_b32_e32 v95, v101
	v_mov_b32_e32 v85, v86
	v_mov_b32_e32 v97, v87
	v_pk_fma_f32 v[60:61], v[62:63], v[66:67], v[98:99] neg_lo:[0,0,1] neg_hi:[0,0,1]
	v_pk_fma_f32 v[52:53], v[54:55], v[66:67], v[74:75]
	v_pk_fma_f32 v[64:65], v[58:59], v[92:93], v[78:79] neg_lo:[0,0,1] neg_hi:[0,0,1]
	v_pk_fma_f32 v[56:57], v[50:51], v[92:93], v[82:83]
	v_pk_add_f32 v[62:63], v[72:73], v[88:89] neg_lo:[0,1] neg_hi:[0,1]
	v_pk_add_f32 v[54:55], v[76:77], v[90:91]
	v_pk_add_f32 v[66:67], v[80:81], v[94:95] neg_lo:[0,1] neg_hi:[0,1]
	v_pk_add_f32 v[58:59], v[84:85], v[96:97]
	s_cbranch_vccnz .LBB0_255
	v_pk_mul_f32 v[62:63], v[62:63], s[28:29] op_sel_hi:[1,0]
	v_pk_mul_f32 v[60:61], v[60:61], s[28:29] op_sel_hi:[1,0]
	v_pk_mul_f32 v[54:55], v[54:55], s[28:29] op_sel_hi:[1,0]
	v_pk_mul_f32 v[52:53], v[52:53], s[28:29] op_sel_hi:[1,0]
	v_pk_mul_f32 v[66:67], v[66:67], s[28:29] op_sel_hi:[1,0]
	v_pk_mul_f32 v[64:65], v[64:65], s[28:29] op_sel_hi:[1,0]
	v_pk_mul_f32 v[58:59], v[58:59], s[28:29] op_sel_hi:[1,0]
	v_pk_mul_f32 v[56:57], v[56:57], s[28:29] op_sel_hi:[1,0]
	s_mov_b64 s[40:41], 0x19300000

; __device__ __forceinline__ u32x4 pack8(const f32x4 a, const f32x4 b) { u32x4 w; w.x = cvt_pk_bf16(a[0], a[1]); w.y = cvt_pk_bf16(a[2], a[3]); w.z = cvt_pk_bf16(b[0], b[1]); w.w = cvt_pk_bf16(b[2], b[3]); return w; }
; __device__ __forceinline__ void rope8(const float* tab64, int row, int fq, const f32x4 x1a, const f32x4 x2a, const f32x4 x1b, const f32x4 x2b, f32x4& a1, f32x4& a2, f32x4& b1, f32x4& b2) {
;     const float* tp = tab64 + ((size_t)pos_index_(row) * 32 + 8 * fq) * 2;
;     const f32x4 c0 = *(const f32x4*)tp, c1 = *(const f32x4*)(tp + 4), c2 = *(const f32x4*)(tp + 8), c3 = *(const f32x4*)(tp + 12);
;     rope4(x1a, x2a, c0, c1, a1, a2); rope4(x1b, x2b, c2, c3, b1, b2);
; }
;     __device__ __forceinline__ void operator()(const f32x4 (&acc)[2][2][4][2], const Unit& u, int wr, int wc, int fr, int fq) const {
;         const int T = u.pn, type = T >> 3; const bool lo = fr < 8;
;         if (MK_EXPG && MK_EXPG != 6 && xskip) return; const bool dry = MK_EXPG == 6 && xskip;
;         const int cw = (T & 7) * 256 + 64 * wc + 8 * fq;
; #pragma unroll
;         for (int ai = 0; ai < 2; ++ai)
; #pragma unroll
;             for (int m = 0; m < 4; ++m) {
;                 const int rowb = u.pm * BM + ai * HALF + wr * 64 + m * 16, row0 = rowb + (fr & 7); const size_t ro0 = (size_t)row0 * 2048;
;                 float* f0 = row0 < 8192 ? (type == 1 ? okp : ovp) + ro0 : (type == 1 ? oks : ovs) + (ro0 - (size_t)8192 * 2048);
;                 if (type < 2) {
;                     f32x4 a1, a2, b1, b2; rope8(tab64, rowb + fr, fq, acc[ai][0][m][0], acc[ai][1][m][0], acc[ai][0][m][1], acc[ai][1][m][1], a1, a2, b1, b2);
;                     if (type == 0) { a1 = a1 * qscale; a2 = a2 * qscale; b1 = b1 * qscale; b2 = b2 * qscale; }
;                     st2_bf16((type == 0 ? QA : KA) + ro0 + cw + (lo ? 0 : 32), 8 * 2048, pack8(a1, b1), pack8(a2, b2), lo, dry);
;                     if (type == 1) { st2_f32<true>(f0 + cw + (lo ? 0 : 4), 8 * 2048, a1, b1, lo, dry); st2_f32<true>(f0 + cw + 32 + (lo ? 0 : 4), 8 * 2048, a2, b2, lo, dry); }
.Lrope_j_p1_5:
	v_mov_b64_e32 v[56:57], v[236:237]
	v_mov_b64_e32 v[58:59], v[238:239]
	v_mov_b64_e32 v[60:61], v[240:241]
	v_mov_b64_e32 v[62:63], v[242:243]
	v_mov_b64_e32 v[64:65], v[244:245]
	v_mov_b64_e32 v[66:67], v[246:247]
	v_mov_b64_e32 v[68:69], v[248:249]
	v_mov_b64_e32 v[70:71], v[250:251]
	s_add_i32 s98, s31, 0xa0
	v_or_b32_e32 v252, s98, v141
	v_bitop3_b32 v253, s98, v165, v141 bitop3:0xc8
	v_and_or_b32 v236, v252, 47, v163
	v_cmp_gt_i32_e32 vcc, s49, v252
	v_readlane_b32 s100, v254, 22
	v_readlane_b32 s101, v254, 23
	v_cndmask_b32_e32 v252, v236, v253, vcc
	v_lshl_or_b32 v252, v252, 8, v168
	s_nop 2
	global_load_dwordx4 v[236:239], v252, s[100:101]
	global_load_dwordx4 v[240:243], v252, s[100:101] offset:16
	global_load_dwordx4 v[244:247], v252, s[100:101] offset:32
	global_load_dwordx4 v[248:251], v252, s[100:101] offset:48
	s_and_b64 vcc, exec, s[6:7]
	s_mov_b64 s[40:41], 0x1b500000
	v_mov_b32_e32 v50, v56
	v_mul_f32_e32 v56, v48, v60
	v_mul_f32_e32 v72, v40, v61
	v_mul_f32_e32 v60, v40, v60
	v_mul_f32_e32 v74, v48, v61
	v_mov_b32_e32 v40, v49
	v_mov_b32_e32 v48, v41
	v_mov_b32_e32 v76, v64
	v_mul_f32_e32 v64, v44, v68
	v_mul_f32_e32 v78, v36, v69
	v_mul_f32_e32 v68, v36, v68
	v_mul_f32_e32 v80, v44, v69
	v_mov_b32_e32 v36, v45
	v_mov_b32_e32 v44, v37
	v_mov_b32_e32 v51, v58
	v_mov_b32_e32 v58, v57
	v_mov_b32_e32 v77, v66
	v_mov_b32_e32 v66, v65
	v_pk_mul_f32 v[40:41], v[40:41], v[62:63]
	v_pk_mul_f32 v[48:49], v[48:49], v[62:63]
	v_pk_mul_f32 v[84:85], v[36:37], v[70:71]
	v_pk_mul_f32 v[70:71], v[44:45], v[70:71]
	v_pk_mul_f32 v[82:83], v[38:39], v[58:59]
	v_pk_mul_f32 v[58:59], v[46:47], v[58:59]
	v_pk_mul_f32 v[62:63], v[34:35], v[66:67]
	v_pk_mul_f32 v[66:67], v[42:43], v[66:67]
	v_mov_b32_e32 v57, v40
	v_mov_b32_e32 v73, v41
	v_mov_b32_e32 v61, v48
	v_mov_b32_e32 v75, v49
	v_mov_b32_e32 v65, v84
	v_mov_b32_e32 v79, v85
	v_mov_b32_e32 v69, v70
	v_mov_b32_e32 v81, v71
	v_pk_fma_f32 v[44:45], v[46:47], v[50:51], v[82:83] neg_lo:[0,0,1] neg_hi:[0,0,1]
	v_pk_fma_f32 v[36:37], v[38:39], v[50:51], v[58:59]
	v_pk_fma_f32 v[48:49], v[42:43], v[76:77], v[62:63] neg_lo:[0,0,1] neg_hi:[0,0,1]
	v_pk_fma_f32 v[40:41], v[34:35], v[76:77], v[66:67]
	v_pk_add_f32 v[46:47], v[56:57], v[72:73] neg_lo:[0,1] neg_hi:[0,1]
	v_pk_add_f32 v[38:39], v[60:61], v[74:75]
	v_pk_add_f32 v[50:51], v[64:65], v[78:79] neg_lo:[0,1] neg_hi:[0,1]
	v_pk_add_f32 v[42:43], v[68:69], v[80:81]
	s_cbranch_vccnz .LBB0_270
	v_pk_mul_f32 v[46:47], v[46:47], s[28:29] op_sel_hi:[1,0]
	v_pk_mul_f32 v[44:45], v[44:45], s[28:29] op_sel_hi:[1,0]
	v_pk_mul_f32 v[38:39], v[38:39], s[28:29] op_sel_hi:[1,0]
	v_pk_mul_f32 v[36:37], v[36:37], s[28:29] op_sel_hi:[1,0]
	v_pk_mul_f32 v[50:51], v[50:51], s[28:29] op_sel_hi:[1,0]
	v_pk_mul_f32 v[48:49], v[48:49], s[28:29] op_sel_hi:[1,0]
	v_pk_mul_f32 v[42:43], v[42:43], s[28:29] op_sel_hi:[1,0]
	v_pk_mul_f32 v[40:41], v[40:41], s[28:29] op_sel_hi:[1,0]
	s_mov_b64 s[40:41], 0x19300000

; __device__ __forceinline__ u32x4 pack8(const f32x4 a, const f32x4 b) { u32x4 w; w.x = cvt_pk_bf16(a[0], a[1]); w.y = cvt_pk_bf16(a[2], a[3]); w.z = cvt_pk_bf16(b[0], b[1]); w.w = cvt_pk_bf16(b[2], b[3]); return w; }
; __device__ __forceinline__ void rope8(const float* tab64, int row, int fq, const f32x4 x1a, const f32x4 x2a, const f32x4 x1b, const f32x4 x2b, f32x4& a1, f32x4& a2, f32x4& b1, f32x4& b2) {
;     const float* tp = tab64 + ((size_t)pos_index_(row) * 32 + 8 * fq) * 2;
;     const f32x4 c0 = *(const f32x4*)tp, c1 = *(const f32x4*)(tp + 4), c2 = *(const f32x4*)(tp + 8), c3 = *(const f32x4*)(tp + 12);
;     rope4(x1a, x2a, c0, c1, a1, a2); rope4(x1b, x2b, c2, c3, b1, b2);
; }
;     __device__ __forceinline__ void operator()(const f32x4 (&acc)[2][2][4][2], const Unit& u, int wr, int wc, int fr, int fq) const {
;         const int T = u.pn, type = T >> 3; const bool lo = fr < 8;
;         if (MK_EXPG && MK_EXPG != 6 && xskip) return; const bool dry = MK_EXPG == 6 && xskip;
;         const int cw = (T & 7) * 256 + 64 * wc + 8 * fq;
; #pragma unroll
;         for (int ai = 0; ai < 2; ++ai)
; #pragma unroll
;             for (int m = 0; m < 4; ++m) {
;                 const int rowb = u.pm * BM + ai * HALF + wr * 64 + m * 16, row0 = rowb + (fr & 7); const size_t ro0 = (size_t)row0 * 2048;
;                 float* f0 = row0 < 8192 ? (type == 1 ? okp : ovp) + ro0 : (type == 1 ? oks : ovs) + (ro0 - (size_t)8192 * 2048);
;                 if (type < 2) {
;                     f32x4 a1, a2, b1, b2; rope8(tab64, rowb + fr, fq, acc[ai][0][m][0], acc[ai][1][m][0], acc[ai][0][m][1], acc[ai][1][m][1], a1, a2, b1, b2);
;                     if (type == 0) { a1 = a1 * qscale; a2 = a2 * qscale; b1 = b1 * qscale; b2 = b2 * qscale; }
;                     st2_bf16((type == 0 ? QA : KA) + ro0 + cw + (lo ? 0 : 32), 8 * 2048, pack8(a1, b1), pack8(a2, b2), lo, dry);
;                     if (type == 1) { st2_f32<true>(f0 + cw + (lo ? 0 : 4), 8 * 2048, a1, b1, lo, dry); st2_f32<true>(f0 + cw + 32 + (lo ? 0 : 4), 8 * 2048, a2, b2, lo, dry); }
.Lrope_j_p1_6:
	v_mov_b64_e32 v[40:41], v[236:237]
	v_mov_b64_e32 v[42:43], v[238:239]
	v_mov_b64_e32 v[44:45], v[240:241]
	v_mov_b64_e32 v[46:47], v[242:243]
	v_mov_b64_e32 v[48:49], v[244:245]
	v_mov_b64_e32 v[50:51], v[246:247]
	v_mov_b64_e32 v[52:53], v[248:249]
	v_mov_b64_e32 v[54:55], v[250:251]
	s_add_i32 s98, s31, 0xb0
	v_or_b32_e32 v252, s98, v141
	v_bitop3_b32 v253, s98, v166, v141 bitop3:0xc8
	v_and_or_b32 v236, v252, 63, v163
	v_cmp_gt_i32_e32 vcc, s49, v252
	v_readlane_b32 s100, v254, 22
	v_readlane_b32 s101, v254, 23
	v_cndmask_b32_e32 v252, v236, v253, vcc
	v_lshl_or_b32 v252, v252, 8, v168
	s_nop 2
	global_load_dwordx4 v[236:239], v252, s[100:101]
	global_load_dwordx4 v[240:243], v252, s[100:101] offset:16
	global_load_dwordx4 v[244:247], v252, s[100:101] offset:32
	global_load_dwordx4 v[248:251], v252, s[100:101] offset:48
	s_and_b64 vcc, exec, s[6:7]
	s_mov_b64 s[40:41], 0x1b500000
	v_mov_b32_e32 v34, v40
	v_mul_f32_e32 v40, v32, v44
	v_mul_f32_e32 v56, v24, v45
	v_mul_f32_e32 v44, v24, v44
	v_mul_f32_e32 v58, v32, v45
	v_mov_b32_e32 v24, v33
	v_mov_b32_e32 v32, v25
	v_mov_b32_e32 v60, v48
	v_mul_f32_e32 v48, v28, v52
	v_mul_f32_e32 v62, v20, v53
	v_mul_f32_e32 v52, v20, v52
	v_mul_f32_e32 v64, v28, v53
	v_mov_b32_e32 v20, v29
	v_mov_b32_e32 v28, v21
	v_mov_b32_e32 v35, v42
	v_mov_b32_e32 v42, v41
	v_mov_b32_e32 v61, v50
	v_mov_b32_e32 v50, v49
	v_pk_mul_f32 v[24:25], v[24:25], v[46:47]
	v_pk_mul_f32 v[32:33], v[32:33], v[46:47]
	v_pk_mul_f32 v[68:69], v[20:21], v[54:55]
	v_pk_mul_f32 v[54:55], v[28:29], v[54:55]
	v_pk_mul_f32 v[66:67], v[22:23], v[42:43]
	v_pk_mul_f32 v[42:43], v[30:31], v[42:43]
	v_pk_mul_f32 v[46:47], v[18:19], v[50:51]
	v_pk_mul_f32 v[50:51], v[26:27], v[50:51]
	v_mov_b32_e32 v41, v24
	v_mov_b32_e32 v57, v25
	v_mov_b32_e32 v45, v32
	v_mov_b32_e32 v59, v33
	v_mov_b32_e32 v49, v68
	v_mov_b32_e32 v63, v69
	v_mov_b32_e32 v53, v54
	v_mov_b32_e32 v65, v55
	v_pk_fma_f32 v[28:29], v[30:31], v[34:35], v[66:67] neg_lo:[0,0,1] neg_hi:[0,0,1]
	v_pk_fma_f32 v[20:21], v[22:23], v[34:35], v[42:43]
	v_pk_fma_f32 v[32:33], v[26:27], v[60:61], v[46:47] neg_lo:[0,0,1] neg_hi:[0,0,1]
	v_pk_fma_f32 v[24:25], v[18:19], v[60:61], v[50:51]
	v_pk_add_f32 v[30:31], v[40:41], v[56:57] neg_lo:[0,1] neg_hi:[0,1]
	v_pk_add_f32 v[22:23], v[44:45], v[58:59]
	v_pk_add_f32 v[34:35], v[48:49], v[62:63] neg_lo:[0,1] neg_hi:[0,1]
	v_pk_add_f32 v[26:27], v[52:53], v[64:65]
	s_cbranch_vccnz .LBB0_285
	v_pk_mul_f32 v[30:31], v[30:31], s[28:29] op_sel_hi:[1,0]
	v_pk_mul_f32 v[28:29], v[28:29], s[28:29] op_sel_hi:[1,0]
	v_pk_mul_f32 v[22:23], v[22:23], s[28:29] op_sel_hi:[1,0]
	v_pk_mul_f32 v[20:21], v[20:21], s[28:29] op_sel_hi:[1,0]
	v_pk_mul_f32 v[34:35], v[34:35], s[28:29] op_sel_hi:[1,0]
	v_pk_mul_f32 v[32:33], v[32:33], s[28:29] op_sel_hi:[1,0]
	v_pk_mul_f32 v[26:27], v[26:27], s[28:29] op_sel_hi:[1,0]
	v_pk_mul_f32 v[24:25], v[24:25], s[28:29] op_sel_hi:[1,0]
	s_mov_b64 s[40:41], 0x19300000

; __device__ __forceinline__ u32x4 pack8(const f32x4 a, const f32x4 b) { u32x4 w; w.x = cvt_pk_bf16(a[0], a[1]); w.y = cvt_pk_bf16(a[2], a[3]); w.z = cvt_pk_bf16(b[0], b[1]); w.w = cvt_pk_bf16(b[2], b[3]); return w; }
; __device__ __forceinline__ void rope8(const float* tab64, int row, int fq, const f32x4 x1a, const f32x4 x2a, const f32x4 x1b, const f32x4 x2b, f32x4& a1, f32x4& a2, f32x4& b1, f32x4& b2) {
;     const float* tp = tab64 + ((size_t)pos_index_(row) * 32 + 8 * fq) * 2;
;     const f32x4 c0 = *(const f32x4*)tp, c1 = *(const f32x4*)(tp + 4), c2 = *(const f32x4*)(tp + 8), c3 = *(const f32x4*)(tp + 12);
;     rope4(x1a, x2a, c0, c1, a1, a2); rope4(x1b, x2b, c2, c3, b1, b2);
; }
;     __device__ __forceinline__ void operator()(const f32x4 (&acc)[2][2][4][2], const Unit& u, int wr, int wc, int fr, int fq) const {
;         const int T = u.pn, type = T >> 3; const bool lo = fr < 8;
;         if (MK_EXPG && MK_EXPG != 6 && xskip) return; const bool dry = MK_EXPG == 6 && xskip;
;         const int cw = (T & 7) * 256 + 64 * wc + 8 * fq;
; #pragma unroll
;         for (int ai = 0; ai < 2; ++ai)
; #pragma unroll
;             for (int m = 0; m < 4; ++m) {
;                 const int rowb = u.pm * BM + ai * HALF + wr * 64 + m * 16, row0 = rowb + (fr & 7); const size_t ro0 = (size_t)row0 * 2048;
;                 float* f0 = row0 < 8192 ? (type == 1 ? okp : ovp) + ro0 : (type == 1 ? oks : ovs) + (ro0 - (size_t)8192 * 2048);
;                 if (type < 2) {
;                     f32x4 a1, a2, b1, b2; rope8(tab64, rowb + fr, fq, acc[ai][0][m][0], acc[ai][1][m][0], acc[ai][0][m][1], acc[ai][1][m][1], a1, a2, b1, b2);
;                     if (type == 0) { a1 = a1 * qscale; a2 = a2 * qscale; b1 = b1 * qscale; b2 = b2 * qscale; }
;                     st2_bf16((type == 0 ? QA : KA) + ro0 + cw + (lo ? 0 : 32), 8 * 2048, pack8(a1, b1), pack8(a2, b2), lo, dry);
;                     if (type == 1) { st2_f32<true>(f0 + cw + (lo ? 0 : 4), 8 * 2048, a1, b1, lo, dry); st2_f32<true>(f0 + cw + 32 + (lo ? 0 : 4), 8 * 2048, a2, b2, lo, dry); }
.LBB0_3100:
	v_cndmask_b32_e64 v130, 0, 1, s[6:7]
	s_andn2_b64 vcc, exec, s[10:11]
	v_lshlrev_b32_e32 v168, 2, v139
	v_cmp_ne_u32_e64 s[6:7], 1, v130
	s_cbranch_vccnz .LBB0_3105
	v_or_b32_e32 v130, s29, v1
	v_bitop3_b32 v131, s29, v160, v1 bitop3:0xc8
	v_cmp_gt_i32_e32 vcc, s47, v130
	v_readlane_b32 s10, v254, 22
	v_readlane_b32 s11, v254, 23
	v_cndmask_b32_e32 v130, v154, v131, vcc
	v_lshl_or_b32 v130, v130, 8, v168
	s_nop 2
	global_load_dwordx4 v[170:173], v130, s[10:11]
	global_load_dwordx4 v[174:177], v130, s[10:11] offset:16
	global_load_dwordx4 v[178:181], v130, s[10:11] offset:32
	global_load_dwordx4 v[182:185], v130, s[10:11] offset:48
	s_add_i32 s98, s31, s66
	v_or_b32_e32 v252, s98, v1
	v_bitop3_b32 v253, s98, v161, v1 bitop3:0xc8
	v_and_or_b32 v236, v252, 31, v162
	v_cmp_gt_i32_e32 vcc, s47, v252
	v_readlane_b32 s100, v254, 22
	v_readlane_b32 s101, v254, 23
	v_cndmask_b32_e32 v252, v236, v253, vcc
	v_lshl_or_b32 v252, v252, 8, v168
	s_nop 2
	global_load_dwordx4 v[236:239], v252, s[100:101]
	global_load_dwordx4 v[240:243], v252, s[100:101] offset:16
	global_load_dwordx4 v[244:247], v252, s[100:101] offset:32
	global_load_dwordx4 v[248:251], v252, s[100:101] offset:48
	s_load_dwordx4 s[72:75], s[88:89], 0xe8
	s_and_b64 vcc, exec, s[6:7]
	s_mov_b64 s[10:11], 0x1b500000
	s_waitcnt vmcnt(4)
	v_mov_b32_e32 v130, v170
	v_mul_f32_e32 v170, v128, v174
	v_mul_f32_e32 v186, v120, v175
	v_mul_f32_e32 v174, v120, v174
	v_mul_f32_e32 v188, v128, v175
	v_mov_b32_e32 v120, v129
	v_mov_b32_e32 v128, v121
	v_mov_b32_e32 v190, v178
	v_mul_f32_e32 v178, v124, v182
	v_mul_f32_e32 v192, v116, v183
	v_mul_f32_e32 v182, v116, v182
	v_mul_f32_e32 v194, v124, v183
	v_mov_b32_e32 v116, v125
	v_mov_b32_e32 v124, v117
	v_mov_b32_e32 v131, v172
	v_mov_b32_e32 v172, v171
	v_mov_b32_e32 v191, v180
	v_mov_b32_e32 v180, v179
	v_pk_mul_f32 v[120:121], v[120:121], v[176:177]
	v_pk_mul_f32 v[128:129], v[128:129], v[176:177]
	v_pk_mul_f32 v[198:199], v[116:117], v[184:185]
	v_pk_mul_f32 v[184:185], v[124:125], v[184:185]
	v_pk_mul_f32 v[196:197], v[118:119], v[172:173]
	v_pk_mul_f32 v[172:173], v[126:127], v[172:173]
	v_pk_mul_f32 v[176:177], v[114:115], v[180:181]
	v_pk_mul_f32 v[180:181], v[122:123], v[180:181]
	v_mov_b32_e32 v171, v120
	v_mov_b32_e32 v187, v121
	v_mov_b32_e32 v175, v128
	v_mov_b32_e32 v189, v129
	v_mov_b32_e32 v179, v198
	v_mov_b32_e32 v193, v199
	v_mov_b32_e32 v183, v184
	v_mov_b32_e32 v195, v185
	v_pk_fma_f32 v[124:125], v[126:127], v[130:131], v[196:197] neg_lo:[0,0,1] neg_hi:[0,0,1]
	v_pk_fma_f32 v[116:117], v[118:119], v[130:131], v[172:173]
	v_pk_fma_f32 v[128:129], v[122:123], v[190:191], v[176:177] neg_lo:[0,0,1] neg_hi:[0,0,1]
	v_pk_fma_f32 v[120:121], v[114:115], v[190:191], v[180:181]
	v_pk_add_f32 v[126:127], v[170:171], v[186:187] neg_lo:[0,1] neg_hi:[0,1]
	v_pk_add_f32 v[118:119], v[174:175], v[188:189]
	v_pk_add_f32 v[130:131], v[178:179], v[192:193] neg_lo:[0,1] neg_hi:[0,1]
	v_pk_add_f32 v[122:123], v[182:183], v[194:195]
	s_cbranch_vccnz .LBB0_3103
	v_pk_mul_f32 v[126:127], v[126:127], s[26:27] op_sel_hi:[1,0]
	v_pk_mul_f32 v[124:125], v[124:125], s[26:27] op_sel_hi:[1,0]
	v_pk_mul_f32 v[118:119], v[118:119], s[26:27] op_sel_hi:[1,0]
	v_pk_mul_f32 v[116:117], v[116:117], s[26:27] op_sel_hi:[1,0]
	v_pk_mul_f32 v[130:131], v[130:131], s[26:27] op_sel_hi:[1,0]
	v_pk_mul_f32 v[128:129], v[128:129], s[26:27] op_sel_hi:[1,0]
	v_pk_mul_f32 v[122:123], v[122:123], s[26:27] op_sel_hi:[1,0]
	v_pk_mul_f32 v[120:121], v[120:121], s[26:27] op_sel_hi:[1,0]
	s_mov_b64 s[10:11], 0x19300000

; __device__ __forceinline__ u32x4 pack8(const f32x4 a, const f32x4 b) { u32x4 w; w.x = cvt_pk_bf16(a[0], a[1]); w.y = cvt_pk_bf16(a[2], a[3]); w.z = cvt_pk_bf16(b[0], b[1]); w.w = cvt_pk_bf16(b[2], b[3]); return w; }
; __device__ __forceinline__ void rope8(const float* tab64, int row, int fq, const f32x4 x1a, const f32x4 x2a, const f32x4 x1b, const f32x4 x2b, f32x4& a1, f32x4& a2, f32x4& b1, f32x4& b2) {
;     const float* tp = tab64 + ((size_t)pos_index_(row) * 32 + 8 * fq) * 2;
;     const f32x4 c0 = *(const f32x4*)tp, c1 = *(const f32x4*)(tp + 4), c2 = *(const f32x4*)(tp + 8), c3 = *(const f32x4*)(tp + 12);
;     rope4(x1a, x2a, c0, c1, a1, a2); rope4(x1b, x2b, c2, c3, b1, b2);
; }
;     __device__ __forceinline__ void operator()(const f32x4 (&acc)[2][2][4][2], const Unit& u, int wr, int wc, int fr, int fq) const {
;         const int T = u.pn, type = T >> 3; const bool lo = fr < 8;
;         if (MK_EXPG && MK_EXPG != 6 && xskip) return; const bool dry = MK_EXPG == 6 && xskip;
;         const int cw = (T & 7) * 256 + 64 * wc + 8 * fq;
; #pragma unroll
;         for (int ai = 0; ai < 2; ++ai)
; #pragma unroll
;             for (int m = 0; m < 4; ++m) {
;                 const int rowb = u.pm * BM + ai * HALF + wr * 64 + m * 16, row0 = rowb + (fr & 7); const size_t ro0 = (size_t)row0 * 2048;
;                 float* f0 = row0 < 8192 ? (type == 1 ? okp : ovp) + ro0 : (type == 1 ? oks : ovs) + (ro0 - (size_t)8192 * 2048);
;                 if (type < 2) {
;                     f32x4 a1, a2, b1, b2; rope8(tab64, rowb + fr, fq, acc[ai][0][m][0], acc[ai][1][m][0], acc[ai][0][m][1], acc[ai][1][m][1], a1, a2, b1, b2);
;                     if (type == 0) { a1 = a1 * qscale; a2 = a2 * qscale; b1 = b1 * qscale; b2 = b2 * qscale; }
;                     st2_bf16((type == 0 ? QA : KA) + ro0 + cw + (lo ? 0 : 32), 8 * 2048, pack8(a1, b1), pack8(a2, b2), lo, dry);
;                     if (type == 1) { st2_f32<true>(f0 + cw + (lo ? 0 : 4), 8 * 2048, a1, b1, lo, dry); st2_f32<true>(f0 + cw + 32 + (lo ? 0 : 4), 8 * 2048, a2, b2, lo, dry); }
.Lrope_j_p18_1:
	v_mov_b64_e32 v[120:121], v[236:237]
	v_mov_b64_e32 v[122:123], v[238:239]
	v_mov_b64_e32 v[124:125], v[240:241]
	v_mov_b64_e32 v[126:127], v[242:243]
	v_mov_b64_e32 v[128:129], v[244:245]
	v_mov_b64_e32 v[130:131], v[246:247]
	v_mov_b64_e32 v[150:151], v[248:249]
	v_mov_b64_e32 v[152:153], v[250:251]
	s_add_i32 s98, s31, s67
	v_or_b32_e32 v252, s98, v1
	v_bitop3_b32 v253, s98, v163, v1 bitop3:0xc8
	v_and_or_b32 v236, v252, 47, v162
	v_cmp_gt_i32_e32 vcc, s47, v252
	v_readlane_b32 s100, v254, 22
	v_readlane_b32 s101, v254, 23
	v_cndmask_b32_e32 v252, v236, v253, vcc
	v_lshl_or_b32 v252, v252, 8, v168
	s_nop 2
	global_load_dwordx4 v[236:239], v252, s[100:101]
	global_load_dwordx4 v[240:243], v252, s[100:101] offset:16
	global_load_dwordx4 v[244:247], v252, s[100:101] offset:32
	global_load_dwordx4 v[248:251], v252, s[100:101] offset:48
	s_and_b64 vcc, exec, s[6:7]
	s_mov_b64 s[38:39], 0x1b500000
	v_mov_b32_e32 v114, v120
	v_mul_f32_e32 v120, v112, v124
	v_mul_f32_e32 v170, v104, v125
	v_mul_f32_e32 v124, v104, v124
	v_mul_f32_e32 v172, v112, v125
	v_mov_b32_e32 v104, v113
	v_mov_b32_e32 v112, v105
	v_mov_b32_e32 v174, v128
	v_mul_f32_e32 v128, v108, v150
	v_mul_f32_e32 v176, v100, v151
	v_mul_f32_e32 v150, v100, v150
	v_mul_f32_e32 v178, v108, v151
	v_mov_b32_e32 v100, v109
	v_mov_b32_e32 v108, v101
	v_mov_b32_e32 v115, v122
	v_mov_b32_e32 v122, v121
	v_mov_b32_e32 v175, v130
	v_mov_b32_e32 v130, v129
	v_pk_mul_f32 v[104:105], v[104:105], v[126:127]
	v_pk_mul_f32 v[112:113], v[112:113], v[126:127]
	v_pk_mul_f32 v[182:183], v[100:101], v[152:153]
	v_pk_mul_f32 v[152:153], v[108:109], v[152:153]
	v_pk_mul_f32 v[180:181], v[102:103], v[122:123]
	v_pk_mul_f32 v[122:123], v[110:111], v[122:123]
	v_pk_mul_f32 v[126:127], v[98:99], v[130:131]
	v_pk_mul_f32 v[130:131], v[106:107], v[130:131]
	v_mov_b32_e32 v121, v104
	v_mov_b32_e32 v171, v105
	v_mov_b32_e32 v125, v112
	v_mov_b32_e32 v173, v113
	v_mov_b32_e32 v129, v182
	v_mov_b32_e32 v177, v183
	v_mov_b32_e32 v151, v152
	v_mov_b32_e32 v179, v153
	v_pk_fma_f32 v[108:109], v[110:111], v[114:115], v[180:181] neg_lo:[0,0,1] neg_hi:[0,0,1]
	v_pk_fma_f32 v[100:101], v[102:103], v[114:115], v[122:123]
	v_pk_fma_f32 v[112:113], v[106:107], v[174:175], v[126:127] neg_lo:[0,0,1] neg_hi:[0,0,1]
	v_pk_fma_f32 v[104:105], v[98:99], v[174:175], v[130:131]
	v_pk_add_f32 v[110:111], v[120:121], v[170:171] neg_lo:[0,1] neg_hi:[0,1]
	v_pk_add_f32 v[102:103], v[124:125], v[172:173]
	v_pk_add_f32 v[114:115], v[128:129], v[176:177] neg_lo:[0,1] neg_hi:[0,1]
	v_pk_add_f32 v[106:107], v[150:151], v[178:179]
	s_cbranch_vccnz .LBB0_3118
	v_pk_mul_f32 v[110:111], v[110:111], s[26:27] op_sel_hi:[1,0]
	v_pk_mul_f32 v[108:109], v[108:109], s[26:27] op_sel_hi:[1,0]
	v_pk_mul_f32 v[102:103], v[102:103], s[26:27] op_sel_hi:[1,0]
	v_pk_mul_f32 v[100:101], v[100:101], s[26:27] op_sel_hi:[1,0]
	v_pk_mul_f32 v[114:115], v[114:115], s[26:27] op_sel_hi:[1,0]
	v_pk_mul_f32 v[112:113], v[112:113], s[26:27] op_sel_hi:[1,0]
	v_pk_mul_f32 v[106:107], v[106:107], s[26:27] op_sel_hi:[1,0]
	v_pk_mul_f32 v[104:105], v[104:105], s[26:27] op_sel_hi:[1,0]
	s_mov_b64 s[38:39], 0x19300000

; __device__ __forceinline__ u32x4 pack8(const f32x4 a, const f32x4 b) { u32x4 w; w.x = cvt_pk_bf16(a[0], a[1]); w.y = cvt_pk_bf16(a[2], a[3]); w.z = cvt_pk_bf16(b[0], b[1]); w.w = cvt_pk_bf16(b[2], b[3]); return w; }
; __device__ __forceinline__ void rope8(const float* tab64, int row, int fq, const f32x4 x1a, const f32x4 x2a, const f32x4 x1b, const f32x4 x2b, f32x4& a1, f32x4& a2, f32x4& b1, f32x4& b2) {
;     const float* tp = tab64 + ((size_t)pos_index_(row) * 32 + 8 * fq) * 2;
;     const f32x4 c0 = *(const f32x4*)tp, c1 = *(const f32x4*)(tp + 4), c2 = *(const f32x4*)(tp + 8), c3 = *(const f32x4*)(tp + 12);
;     rope4(x1a, x2a, c0, c1, a1, a2); rope4(x1b, x2b, c2, c3, b1, b2);
; }
;     __device__ __forceinline__ void operator()(const f32x4 (&acc)[2][2][4][2], const Unit& u, int wr, int wc, int fr, int fq) const {
;         const int T = u.pn, type = T >> 3; const bool lo = fr < 8;
;         if (MK_EXPG && MK_EXPG != 6 && xskip) return; const bool dry = MK_EXPG == 6 && xskip;
;         const int cw = (T & 7) * 256 + 64 * wc + 8 * fq;
; #pragma unroll
;         for (int ai = 0; ai < 2; ++ai)
; #pragma unroll
;             for (int m = 0; m < 4; ++m) {
;                 const int rowb = u.pm * BM + ai * HALF + wr * 64 + m * 16, row0 = rowb + (fr & 7); const size_t ro0 = (size_t)row0 * 2048;
;                 float* f0 = row0 < 8192 ? (type == 1 ? okp : ovp) + ro0 : (type == 1 ? oks : ovs) + (ro0 - (size_t)8192 * 2048);
;                 if (type < 2) {
;                     f32x4 a1, a2, b1, b2; rope8(tab64, rowb + fr, fq, acc[ai][0][m][0], acc[ai][1][m][0], acc[ai][0][m][1], acc[ai][1][m][1], a1, a2, b1, b2);
;                     if (type == 0) { a1 = a1 * qscale; a2 = a2 * qscale; b1 = b1 * qscale; b2 = b2 * qscale; }
;                     st2_bf16((type == 0 ? QA : KA) + ro0 + cw + (lo ? 0 : 32), 8 * 2048, pack8(a1, b1), pack8(a2, b2), lo, dry);
;                     if (type == 1) { st2_f32<true>(f0 + cw + (lo ? 0 : 4), 8 * 2048, a1, b1, lo, dry); st2_f32<true>(f0 + cw + 32 + (lo ? 0 : 4), 8 * 2048, a2, b2, lo, dry); }
.Lrope_j_p18_2:
	v_mov_b64_e32 v[104:105], v[236:237]
	v_mov_b64_e32 v[106:107], v[238:239]
	v_mov_b64_e32 v[108:109], v[240:241]
	v_mov_b64_e32 v[110:111], v[242:243]
	v_mov_b64_e32 v[112:113], v[244:245]
	v_mov_b64_e32 v[114:115], v[246:247]
	v_mov_b64_e32 v[116:117], v[248:249]
	v_mov_b64_e32 v[118:119], v[250:251]
	s_add_i32 s98, s31, s68
	v_or_b32_e32 v252, s98, v1
	v_bitop3_b32 v253, s98, v166, v1 bitop3:0xc8
	v_and_or_b32 v236, v252, 63, v162
	v_cmp_gt_i32_e32 vcc, s47, v252
	v_readlane_b32 s100, v254, 22
	v_readlane_b32 s101, v254, 23
	v_cndmask_b32_e32 v252, v236, v253, vcc
	v_lshl_or_b32 v252, v252, 8, v168
	s_nop 2
	global_load_dwordx4 v[236:239], v252, s[100:101]
	global_load_dwordx4 v[240:243], v252, s[100:101] offset:16
	global_load_dwordx4 v[244:247], v252, s[100:101] offset:32
	global_load_dwordx4 v[248:251], v252, s[100:101] offset:48
	s_and_b64 vcc, exec, s[6:7]
	s_mov_b64 s[38:39], 0x1b500000
	v_mov_b32_e32 v98, v104
	v_mul_f32_e32 v104, v96, v108
	v_mul_f32_e32 v120, v88, v109
	v_mul_f32_e32 v108, v88, v108
	v_mul_f32_e32 v122, v96, v109
	v_mov_b32_e32 v88, v97
	v_mov_b32_e32 v96, v89
	v_mov_b32_e32 v124, v112
	v_mul_f32_e32 v112, v92, v116
	v_mul_f32_e32 v126, v84, v117
	v_mul_f32_e32 v116, v84, v116
	v_mul_f32_e32 v128, v92, v117
	v_mov_b32_e32 v84, v93
	v_mov_b32_e32 v92, v85
	v_mov_b32_e32 v99, v106
	v_mov_b32_e32 v106, v105
	v_mov_b32_e32 v125, v114
	v_mov_b32_e32 v114, v113
	v_pk_mul_f32 v[88:89], v[88:89], v[110:111]
	v_pk_mul_f32 v[96:97], v[96:97], v[110:111]
	v_pk_mul_f32 v[150:151], v[84:85], v[118:119]
	v_pk_mul_f32 v[118:119], v[92:93], v[118:119]
	v_pk_mul_f32 v[130:131], v[86:87], v[106:107]
	v_pk_mul_f32 v[106:107], v[94:95], v[106:107]
	v_pk_mul_f32 v[110:111], v[82:83], v[114:115]
	v_pk_mul_f32 v[114:115], v[90:91], v[114:115]
	v_mov_b32_e32 v105, v88
	v_mov_b32_e32 v121, v89
	v_mov_b32_e32 v109, v96
	v_mov_b32_e32 v123, v97
	v_mov_b32_e32 v113, v150
	v_mov_b32_e32 v127, v151
	v_mov_b32_e32 v117, v118
	v_mov_b32_e32 v129, v119
	v_pk_fma_f32 v[92:93], v[94:95], v[98:99], v[130:131] neg_lo:[0,0,1] neg_hi:[0,0,1]
	v_pk_fma_f32 v[84:85], v[86:87], v[98:99], v[106:107]
	v_pk_fma_f32 v[96:97], v[90:91], v[124:125], v[110:111] neg_lo:[0,0,1] neg_hi:[0,0,1]
	v_pk_fma_f32 v[88:89], v[82:83], v[124:125], v[114:115]
	v_pk_add_f32 v[94:95], v[104:105], v[120:121] neg_lo:[0,1] neg_hi:[0,1]
	v_pk_add_f32 v[86:87], v[108:109], v[122:123]
	v_pk_add_f32 v[98:99], v[112:113], v[126:127] neg_lo:[0,1] neg_hi:[0,1]
	v_pk_add_f32 v[90:91], v[116:117], v[128:129]
	s_cbranch_vccnz .LBB0_3133
	v_pk_mul_f32 v[94:95], v[94:95], s[26:27] op_sel_hi:[1,0]
	v_pk_mul_f32 v[92:93], v[92:93], s[26:27] op_sel_hi:[1,0]
	v_pk_mul_f32 v[86:87], v[86:87], s[26:27] op_sel_hi:[1,0]
	v_pk_mul_f32 v[84:85], v[84:85], s[26:27] op_sel_hi:[1,0]
	v_pk_mul_f32 v[98:99], v[98:99], s[26:27] op_sel_hi:[1,0]
	v_pk_mul_f32 v[96:97], v[96:97], s[26:27] op_sel_hi:[1,0]
	v_pk_mul_f32 v[90:91], v[90:91], s[26:27] op_sel_hi:[1,0]
	v_pk_mul_f32 v[88:89], v[88:89], s[26:27] op_sel_hi:[1,0]
	s_mov_b64 s[38:39], 0x19300000

; __device__ __forceinline__ u32x4 pack8(const f32x4 a, const f32x4 b) { u32x4 w; w.x = cvt_pk_bf16(a[0], a[1]); w.y = cvt_pk_bf16(a[2], a[3]); w.z = cvt_pk_bf16(b[0], b[1]); w.w = cvt_pk_bf16(b[2], b[3]); return w; }
; __device__ __forceinline__ void rope8(const float* tab64, int row, int fq, const f32x4 x1a, const f32x4 x2a, const f32x4 x1b, const f32x4 x2b, f32x4& a1, f32x4& a2, f32x4& b1, f32x4& b2) {
;     const float* tp = tab64 + ((size_t)pos_index_(row) * 32 + 8 * fq) * 2;
;     const f32x4 c0 = *(const f32x4*)tp, c1 = *(const f32x4*)(tp + 4), c2 = *(const f32x4*)(tp + 8), c3 = *(const f32x4*)(tp + 12);
;     rope4(x1a, x2a, c0, c1, a1, a2); rope4(x1b, x2b, c2, c3, b1, b2);
; }
;     __device__ __forceinline__ void operator()(const f32x4 (&acc)[2][2][4][2], const Unit& u, int wr, int wc, int fr, int fq) const {
;         const int T = u.pn, type = T >> 3; const bool lo = fr < 8;
;         if (MK_EXPG && MK_EXPG != 6 && xskip) return; const bool dry = MK_EXPG == 6 && xskip;
;         const int cw = (T & 7) * 256 + 64 * wc + 8 * fq;
; #pragma unroll
;         for (int ai = 0; ai < 2; ++ai)
; #pragma unroll
;             for (int m = 0; m < 4; ++m) {
;                 const int rowb = u.pm * BM + ai * HALF + wr * 64 + m * 16, row0 = rowb + (fr & 7); const size_t ro0 = (size_t)row0 * 2048;
;                 float* f0 = row0 < 8192 ? (type == 1 ? okp : ovp) + ro0 : (type == 1 ? oks : ovs) + (ro0 - (size_t)8192 * 2048);
;                 if (type < 2) {
;                     f32x4 a1, a2, b1, b2; rope8(tab64, rowb + fr, fq, acc[ai][0][m][0], acc[ai][1][m][0], acc[ai][0][m][1], acc[ai][1][m][1], a1, a2, b1, b2);
;                     if (type == 0) { a1 = a1 * qscale; a2 = a2 * qscale; b1 = b1 * qscale; b2 = b2 * qscale; }
;                     st2_bf16((type == 0 ? QA : KA) + ro0 + cw + (lo ? 0 : 32), 8 * 2048, pack8(a1, b1), pack8(a2, b2), lo, dry);
;                     if (type == 1) { st2_f32<true>(f0 + cw + (lo ? 0 : 4), 8 * 2048, a1, b1, lo, dry); st2_f32<true>(f0 + cw + 32 + (lo ? 0 : 4), 8 * 2048, a2, b2, lo, dry); }
.Lrope_j_p18_3:
	v_mov_b64_e32 v[88:89], v[236:237]
	v_mov_b64_e32 v[90:91], v[238:239]
	v_mov_b64_e32 v[92:93], v[240:241]
	v_mov_b64_e32 v[94:95], v[242:243]
	v_mov_b64_e32 v[96:97], v[244:245]
	v_mov_b64_e32 v[98:99], v[246:247]
	v_mov_b64_e32 v[100:101], v[248:249]
	v_mov_b64_e32 v[102:103], v[250:251]
	s_add_i32 s98, s29, 0x80
	v_or_b32_e32 v252, s98, v1
	v_bitop3_b32 v253, s98, v160, v1 bitop3:0xc8
	v_cmp_gt_i32_e32 vcc, s47, v252
	v_readlane_b32 s100, v254, 22
	v_readlane_b32 s101, v254, 23
	v_cndmask_b32_e32 v252, v154, v253, vcc
	v_lshl_or_b32 v252, v252, 8, v168
	s_nop 2
	global_load_dwordx4 v[236:239], v252, s[100:101]
	global_load_dwordx4 v[240:243], v252, s[100:101] offset:16
	global_load_dwordx4 v[244:247], v252, s[100:101] offset:32
	global_load_dwordx4 v[248:251], v252, s[100:101] offset:48
	s_and_b64 vcc, exec, s[6:7]
	s_mov_b64 s[38:39], 0x1b500000
	v_mov_b32_e32 v82, v88
	v_mul_f32_e32 v88, v80, v92
	v_mul_f32_e32 v104, v72, v93
	v_mul_f32_e32 v92, v72, v92
	v_mul_f32_e32 v106, v80, v93
	v_mov_b32_e32 v72, v81
	v_mov_b32_e32 v80, v73
	v_mov_b32_e32 v108, v96
	v_mul_f32_e32 v96, v76, v100
	v_mul_f32_e32 v110, v68, v101
	v_mul_f32_e32 v100, v68, v100
	v_mul_f32_e32 v112, v76, v101
	v_mov_b32_e32 v68, v77
	v_mov_b32_e32 v76, v69
	v_mov_b32_e32 v83, v90
	v_mov_b32_e32 v90, v89
	v_mov_b32_e32 v109, v98
	v_mov_b32_e32 v98, v97
	v_pk_mul_f32 v[72:73], v[72:73], v[94:95]
	v_pk_mul_f32 v[80:81], v[80:81], v[94:95]
	v_pk_mul_f32 v[116:117], v[68:69], v[102:103]
	v_pk_mul_f32 v[102:103], v[76:77], v[102:103]
	v_pk_mul_f32 v[114:115], v[70:71], v[90:91]
	v_pk_mul_f32 v[90:91], v[78:79], v[90:91]
	v_pk_mul_f32 v[94:95], v[66:67], v[98:99]
	v_pk_mul_f32 v[98:99], v[74:75], v[98:99]
	v_mov_b32_e32 v89, v72
	v_mov_b32_e32 v105, v73
	v_mov_b32_e32 v93, v80
	v_mov_b32_e32 v107, v81
	v_mov_b32_e32 v97, v116
	v_mov_b32_e32 v111, v117
	v_mov_b32_e32 v101, v102
	v_mov_b32_e32 v113, v103
	v_pk_fma_f32 v[76:77], v[78:79], v[82:83], v[114:115] neg_lo:[0,0,1] neg_hi:[0,0,1]
	v_pk_fma_f32 v[68:69], v[70:71], v[82:83], v[90:91]
	v_pk_fma_f32 v[80:81], v[74:75], v[108:109], v[94:95] neg_lo:[0,0,1] neg_hi:[0,0,1]
	v_pk_fma_f32 v[72:73], v[66:67], v[108:109], v[98:99]
	v_pk_add_f32 v[78:79], v[88:89], v[104:105] neg_lo:[0,1] neg_hi:[0,1]
	v_pk_add_f32 v[70:71], v[92:93], v[106:107]
	v_pk_add_f32 v[82:83], v[96:97], v[110:111] neg_lo:[0,1] neg_hi:[0,1]
	v_pk_add_f32 v[74:75], v[100:101], v[112:113]
	s_cbranch_vccnz .LBB0_3148
	v_pk_mul_f32 v[78:79], v[78:79], s[26:27] op_sel_hi:[1,0]
	v_pk_mul_f32 v[76:77], v[76:77], s[26:27] op_sel_hi:[1,0]
	v_pk_mul_f32 v[70:71], v[70:71], s[26:27] op_sel_hi:[1,0]
	v_pk_mul_f32 v[68:69], v[68:69], s[26:27] op_sel_hi:[1,0]
	v_pk_mul_f32 v[82:83], v[82:83], s[26:27] op_sel_hi:[1,0]
	v_pk_mul_f32 v[80:81], v[80:81], s[26:27] op_sel_hi:[1,0]
	v_pk_mul_f32 v[74:75], v[74:75], s[26:27] op_sel_hi:[1,0]
	v_pk_mul_f32 v[72:73], v[72:73], s[26:27] op_sel_hi:[1,0]
	s_mov_b64 s[38:39], 0x19300000

; __device__ __forceinline__ u32x4 pack8(const f32x4 a, const f32x4 b) { u32x4 w; w.x = cvt_pk_bf16(a[0], a[1]); w.y = cvt_pk_bf16(a[2], a[3]); w.z = cvt_pk_bf16(b[0], b[1]); w.w = cvt_pk_bf16(b[2], b[3]); return w; }
; __device__ __forceinline__ void rope8(const float* tab64, int row, int fq, const f32x4 x1a, const f32x4 x2a, const f32x4 x1b, const f32x4 x2b, f32x4& a1, f32x4& a2, f32x4& b1, f32x4& b2) {
;     const float* tp = tab64 + ((size_t)pos_index_(row) * 32 + 8 * fq) * 2;
;     const f32x4 c0 = *(const f32x4*)tp, c1 = *(const f32x4*)(tp + 4), c2 = *(const f32x4*)(tp + 8), c3 = *(const f32x4*)(tp + 12);
;     rope4(x1a, x2a, c0, c1, a1, a2); rope4(x1b, x2b, c2, c3, b1, b2);
; }
;     __device__ __forceinline__ void operator()(const f32x4 (&acc)[2][2][4][2], const Unit& u, int wr, int wc, int fr, int fq) const {
;         const int T = u.pn, type = T >> 3; const bool lo = fr < 8;
;         if (MK_EXPG && MK_EXPG != 6 && xskip) return; const bool dry = MK_EXPG == 6 && xskip;
;         const int cw = (T & 7) * 256 + 64 * wc + 8 * fq;
; #pragma unroll
;         for (int ai = 0; ai < 2; ++ai)
; #pragma unroll
;             for (int m = 0; m < 4; ++m) {
;                 const int rowb = u.pm * BM + ai * HALF + wr * 64 + m * 16, row0 = rowb + (fr & 7); const size_t ro0 = (size_t)row0 * 2048;
;                 float* f0 = row0 < 8192 ? (type == 1 ? okp : ovp) + ro0 : (type == 1 ? oks : ovs) + (ro0 - (size_t)8192 * 2048);
;                 if (type < 2) {
;                     f32x4 a1, a2, b1, b2; rope8(tab64, rowb + fr, fq, acc[ai][0][m][0], acc[ai][1][m][0], acc[ai][0][m][1], acc[ai][1][m][1], a1, a2, b1, b2);
;                     if (type == 0) { a1 = a1 * qscale; a2 = a2 * qscale; b1 = b1 * qscale; b2 = b2 * qscale; }
;                     st2_bf16((type == 0 ? QA : KA) + ro0 + cw + (lo ? 0 : 32), 8 * 2048, pack8(a1, b1), pack8(a2, b2), lo, dry);
;                     if (type == 1) { st2_f32<true>(f0 + cw + (lo ? 0 : 4), 8 * 2048, a1, b1, lo, dry); st2_f32<true>(f0 + cw + 32 + (lo ? 0 : 4), 8 * 2048, a2, b2, lo, dry); }
.Lrope_j_p18_4:
	v_mov_b64_e32 v[72:73], v[236:237]
	v_mov_b64_e32 v[74:75], v[238:239]
	v_mov_b64_e32 v[76:77], v[240:241]
	v_mov_b64_e32 v[78:79], v[242:243]
	v_mov_b64_e32 v[80:81], v[244:245]
	v_mov_b64_e32 v[82:83], v[246:247]
	v_mov_b64_e32 v[84:85], v[248:249]
	v_mov_b64_e32 v[86:87], v[250:251]
	s_add_i32 s98, s29, 0x90
	v_or_b32_e32 v252, s98, v1
	v_bitop3_b32 v253, s98, v161, v1 bitop3:0xc8
	v_and_or_b32 v236, v252, 31, v162
	v_cmp_gt_i32_e32 vcc, s47, v252
	v_readlane_b32 s100, v254, 22
	v_readlane_b32 s101, v254, 23
	v_cndmask_b32_e32 v252, v236, v253, vcc
	v_lshl_or_b32 v252, v252, 8, v168
	s_nop 2
	global_load_dwordx4 v[236:239], v252, s[100:101]
	global_load_dwordx4 v[240:243], v252, s[100:101] offset:16
	global_load_dwordx4 v[244:247], v252, s[100:101] offset:32
	global_load_dwordx4 v[248:251], v252, s[100:101] offset:48
	s_and_b64 vcc, exec, s[6:7]
	s_mov_b64 s[38:39], 0x1b500000
	v_mov_b32_e32 v66, v72
	v_mul_f32_e32 v72, v64, v76
	v_mul_f32_e32 v88, v56, v77
	v_mul_f32_e32 v76, v56, v76
	v_mul_f32_e32 v90, v64, v77
	v_mov_b32_e32 v56, v65
	v_mov_b32_e32 v64, v57
	v_mov_b32_e32 v92, v80
	v_mul_f32_e32 v80, v60, v84
	v_mul_f32_e32 v94, v52, v85
	v_mul_f32_e32 v84, v52, v84
	v_mul_f32_e32 v96, v60, v85
	v_mov_b32_e32 v52, v61
	v_mov_b32_e32 v60, v53
	v_mov_b32_e32 v67, v74
	v_mov_b32_e32 v74, v73
	v_mov_b32_e32 v93, v82
	v_mov_b32_e32 v82, v81
	v_pk_mul_f32 v[56:57], v[56:57], v[78:79]
	v_pk_mul_f32 v[64:65], v[64:65], v[78:79]
	v_pk_mul_f32 v[100:101], v[52:53], v[86:87]
	v_pk_mul_f32 v[86:87], v[60:61], v[86:87]
	v_pk_mul_f32 v[98:99], v[54:55], v[74:75]
	v_pk_mul_f32 v[74:75], v[62:63], v[74:75]
	v_pk_mul_f32 v[78:79], v[50:51], v[82:83]
	v_pk_mul_f32 v[82:83], v[58:59], v[82:83]
	v_mov_b32_e32 v73, v56
	v_mov_b32_e32 v89, v57
	v_mov_b32_e32 v77, v64
	v_mov_b32_e32 v91, v65
	v_mov_b32_e32 v81, v100
	v_mov_b32_e32 v95, v101
	v_mov_b32_e32 v85, v86
	v_mov_b32_e32 v97, v87
	v_pk_fma_f32 v[60:61], v[62:63], v[66:67], v[98:99] neg_lo:[0,0,1] neg_hi:[0,0,1]
	v_pk_fma_f32 v[52:53], v[54:55], v[66:67], v[74:75]
	v_pk_fma_f32 v[64:65], v[58:59], v[92:93], v[78:79] neg_lo:[0,0,1] neg_hi:[0,0,1]
	v_pk_fma_f32 v[56:57], v[50:51], v[92:93], v[82:83]
	v_pk_add_f32 v[62:63], v[72:73], v[88:89] neg_lo:[0,1] neg_hi:[0,1]
	v_pk_add_f32 v[54:55], v[76:77], v[90:91]
	v_pk_add_f32 v[66:67], v[80:81], v[94:95] neg_lo:[0,1] neg_hi:[0,1]
	v_pk_add_f32 v[58:59], v[84:85], v[96:97]
	s_cbranch_vccnz .LBB0_3163
	v_pk_mul_f32 v[62:63], v[62:63], s[26:27] op_sel_hi:[1,0]
	v_pk_mul_f32 v[60:61], v[60:61], s[26:27] op_sel_hi:[1,0]
	v_pk_mul_f32 v[54:55], v[54:55], s[26:27] op_sel_hi:[1,0]
	v_pk_mul_f32 v[52:53], v[52:53], s[26:27] op_sel_hi:[1,0]
	v_pk_mul_f32 v[66:67], v[66:67], s[26:27] op_sel_hi:[1,0]
	v_pk_mul_f32 v[64:65], v[64:65], s[26:27] op_sel_hi:[1,0]
	v_pk_mul_f32 v[58:59], v[58:59], s[26:27] op_sel_hi:[1,0]
	v_pk_mul_f32 v[56:57], v[56:57], s[26:27] op_sel_hi:[1,0]
	s_mov_b64 s[38:39], 0x19300000

; __device__ __forceinline__ u32x4 pack8(const f32x4 a, const f32x4 b) { u32x4 w; w.x = cvt_pk_bf16(a[0], a[1]); w.y = cvt_pk_bf16(a[2], a[3]); w.z = cvt_pk_bf16(b[0], b[1]); w.w = cvt_pk_bf16(b[2], b[3]); return w; }
; __device__ __forceinline__ void rope8(const float* tab64, int row, int fq, const f32x4 x1a, const f32x4 x2a, const f32x4 x1b, const f32x4 x2b, f32x4& a1, f32x4& a2, f32x4& b1, f32x4& b2) {
;     const float* tp = tab64 + ((size_t)pos_index_(row) * 32 + 8 * fq) * 2;
;     const f32x4 c0 = *(const f32x4*)tp, c1 = *(const f32x4*)(tp + 4), c2 = *(const f32x4*)(tp + 8), c3 = *(const f32x4*)(tp + 12);
;     rope4(x1a, x2a, c0, c1, a1, a2); rope4(x1b, x2b, c2, c3, b1, b2);
; }
;     __device__ __forceinline__ void operator()(const f32x4 (&acc)[2][2][4][2], const Unit& u, int wr, int wc, int fr, int fq) const {
;         const int T = u.pn, type = T >> 3; const bool lo = fr < 8;
;         if (MK_EXPG && MK_EXPG != 6 && xskip) return; const bool dry = MK_EXPG == 6 && xskip;
;         const int cw = (T & 7) * 256 + 64 * wc + 8 * fq;
; #pragma unroll
;         for (int ai = 0; ai < 2; ++ai)
; #pragma unroll
;             for (int m = 0; m < 4; ++m) {
;                 const int rowb = u.pm * BM + ai * HALF + wr * 64 + m * 16, row0 = rowb + (fr & 7); const size_t ro0 = (size_t)row0 * 2048;
;                 float* f0 = row0 < 8192 ? (type == 1 ? okp : ovp) + ro0 : (type == 1 ? oks : ovs) + (ro0 - (size_t)8192 * 2048);
;                 if (type < 2) {
;                     f32x4 a1, a2, b1, b2; rope8(tab64, rowb + fr, fq, acc[ai][0][m][0], acc[ai][1][m][0], acc[ai][0][m][1], acc[ai][1][m][1], a1, a2, b1, b2);
;                     if (type == 0) { a1 = a1 * qscale; a2 = a2 * qscale; b1 = b1 * qscale; b2 = b2 * qscale; }
;                     st2_bf16((type == 0 ? QA : KA) + ro0 + cw + (lo ? 0 : 32), 8 * 2048, pack8(a1, b1), pack8(a2, b2), lo, dry);
;                     if (type == 1) { st2_f32<true>(f0 + cw + (lo ? 0 : 4), 8 * 2048, a1, b1, lo, dry); st2_f32<true>(f0 + cw + 32 + (lo ? 0 : 4), 8 * 2048, a2, b2, lo, dry); }
.Lrope_j_p18_5:
	v_mov_b64_e32 v[56:57], v[236:237]
	v_mov_b64_e32 v[58:59], v[238:239]
	v_mov_b64_e32 v[60:61], v[240:241]
	v_mov_b64_e32 v[62:63], v[242:243]
	v_mov_b64_e32 v[64:65], v[244:245]
	v_mov_b64_e32 v[66:67], v[246:247]
	v_mov_b64_e32 v[68:69], v[248:249]
	v_mov_b64_e32 v[70:71], v[250:251]
	s_add_i32 s98, s29, 0xa0
	v_or_b32_e32 v252, s98, v1
	v_bitop3_b32 v253, s98, v163, v1 bitop3:0xc8
	v_and_or_b32 v236, v252, 47, v162
	v_cmp_gt_i32_e32 vcc, s47, v252
	v_readlane_b32 s100, v254, 22
	v_readlane_b32 s101, v254, 23
	v_cndmask_b32_e32 v252, v236, v253, vcc
	v_lshl_or_b32 v252, v252, 8, v168
	s_nop 2
	global_load_dwordx4 v[236:239], v252, s[100:101]
	global_load_dwordx4 v[240:243], v252, s[100:101] offset:16
	global_load_dwordx4 v[244:247], v252, s[100:101] offset:32
	global_load_dwordx4 v[248:251], v252, s[100:101] offset:48
	s_and_b64 vcc, exec, s[6:7]
	s_mov_b64 s[38:39], 0x1b500000
	v_mov_b32_e32 v50, v56
	v_mul_f32_e32 v56, v48, v60
	v_mul_f32_e32 v72, v40, v61
	v_mul_f32_e32 v60, v40, v60
	v_mul_f32_e32 v74, v48, v61
	v_mov_b32_e32 v40, v49
	v_mov_b32_e32 v48, v41
	v_mov_b32_e32 v76, v64
	v_mul_f32_e32 v64, v44, v68
	v_mul_f32_e32 v78, v36, v69
	v_mul_f32_e32 v68, v36, v68
	v_mul_f32_e32 v80, v44, v69
	v_mov_b32_e32 v36, v45
	v_mov_b32_e32 v44, v37
	v_mov_b32_e32 v51, v58
	v_mov_b32_e32 v58, v57
	v_mov_b32_e32 v77, v66
	v_mov_b32_e32 v66, v65
	v_pk_mul_f32 v[40:41], v[40:41], v[62:63]
	v_pk_mul_f32 v[48:49], v[48:49], v[62:63]
	v_pk_mul_f32 v[84:85], v[36:37], v[70:71]
	v_pk_mul_f32 v[70:71], v[44:45], v[70:71]
	v_pk_mul_f32 v[82:83], v[38:39], v[58:59]
	v_pk_mul_f32 v[58:59], v[46:47], v[58:59]
	v_pk_mul_f32 v[62:63], v[34:35], v[66:67]
	v_pk_mul_f32 v[66:67], v[42:43], v[66:67]
	v_mov_b32_e32 v57, v40
	v_mov_b32_e32 v73, v41
	v_mov_b32_e32 v61, v48
	v_mov_b32_e32 v75, v49
	v_mov_b32_e32 v65, v84
	v_mov_b32_e32 v79, v85
	v_mov_b32_e32 v69, v70
	v_mov_b32_e32 v81, v71
	v_pk_fma_f32 v[44:45], v[46:47], v[50:51], v[82:83] neg_lo:[0,0,1] neg_hi:[0,0,1]
	v_pk_fma_f32 v[36:37], v[38:39], v[50:51], v[58:59]
	v_pk_fma_f32 v[48:49], v[42:43], v[76:77], v[62:63] neg_lo:[0,0,1] neg_hi:[0,0,1]
	v_pk_fma_f32 v[40:41], v[34:35], v[76:77], v[66:67]
	v_pk_add_f32 v[46:47], v[56:57], v[72:73] neg_lo:[0,1] neg_hi:[0,1]
	v_pk_add_f32 v[38:39], v[60:61], v[74:75]
	v_pk_add_f32 v[50:51], v[64:65], v[78:79] neg_lo:[0,1] neg_hi:[0,1]
	v_pk_add_f32 v[42:43], v[68:69], v[80:81]
	s_cbranch_vccnz .LBB0_3178
	v_pk_mul_f32 v[46:47], v[46:47], s[26:27] op_sel_hi:[1,0]
	v_pk_mul_f32 v[44:45], v[44:45], s[26:27] op_sel_hi:[1,0]
	v_pk_mul_f32 v[38:39], v[38:39], s[26:27] op_sel_hi:[1,0]
	v_pk_mul_f32 v[36:37], v[36:37], s[26:27] op_sel_hi:[1,0]
	v_pk_mul_f32 v[50:51], v[50:51], s[26:27] op_sel_hi:[1,0]
	v_pk_mul_f32 v[48:49], v[48:49], s[26:27] op_sel_hi:[1,0]
	v_pk_mul_f32 v[42:43], v[42:43], s[26:27] op_sel_hi:[1,0]
	v_pk_mul_f32 v[40:41], v[40:41], s[26:27] op_sel_hi:[1,0]
	s_mov_b64 s[38:39], 0x19300000

; __device__ __forceinline__ u32x4 pack8(const f32x4 a, const f32x4 b) { u32x4 w; w.x = cvt_pk_bf16(a[0], a[1]); w.y = cvt_pk_bf16(a[2], a[3]); w.z = cvt_pk_bf16(b[0], b[1]); w.w = cvt_pk_bf16(b[2], b[3]); return w; }
; __device__ __forceinline__ void rope8(const float* tab64, int row, int fq, const f32x4 x1a, const f32x4 x2a, const f32x4 x1b, const f32x4 x2b, f32x4& a1, f32x4& a2, f32x4& b1, f32x4& b2) {
;     const float* tp = tab64 + ((size_t)pos_index_(row) * 32 + 8 * fq) * 2;
;     const f32x4 c0 = *(const f32x4*)tp, c1 = *(const f32x4*)(tp + 4), c2 = *(const f32x4*)(tp + 8), c3 = *(const f32x4*)(tp + 12);
;     rope4(x1a, x2a, c0, c1, a1, a2); rope4(x1b, x2b, c2, c3, b1, b2);
; }
;     __device__ __forceinline__ void operator()(const f32x4 (&acc)[2][2][4][2], const Unit& u, int wr, int wc, int fr, int fq) const {
;         const int T = u.pn, type = T >> 3; const bool lo = fr < 8;
;         if (MK_EXPG && MK_EXPG != 6 && xskip) return; const bool dry = MK_EXPG == 6 && xskip;
;         const int cw = (T & 7) * 256 + 64 * wc + 8 * fq;
; #pragma unroll
;         for (int ai = 0; ai < 2; ++ai)
; #pragma unroll
;             for (int m = 0; m < 4; ++m) {
;                 const int rowb = u.pm * BM + ai * HALF + wr * 64 + m * 16, row0 = rowb + (fr & 7); const size_t ro0 = (size_t)row0 * 2048;
;                 float* f0 = row0 < 8192 ? (type == 1 ? okp : ovp) + ro0 : (type == 1 ? oks : ovs) + (ro0 - (size_t)8192 * 2048);
;                 if (type < 2) {
;                     f32x4 a1, a2, b1, b2; rope8(tab64, rowb + fr, fq, acc[ai][0][m][0], acc[ai][1][m][0], acc[ai][0][m][1], acc[ai][1][m][1], a1, a2, b1, b2);
;                     if (type == 0) { a1 = a1 * qscale; a2 = a2 * qscale; b1 = b1 * qscale; b2 = b2 * qscale; }
;                     st2_bf16((type == 0 ? QA : KA) + ro0 + cw + (lo ? 0 : 32), 8 * 2048, pack8(a1, b1), pack8(a2, b2), lo, dry);
;                     if (type == 1) { st2_f32<true>(f0 + cw + (lo ? 0 : 4), 8 * 2048, a1, b1, lo, dry); st2_f32<true>(f0 + cw + 32 + (lo ? 0 : 4), 8 * 2048, a2, b2, lo, dry); }
.Lrope_j_p18_6:
	v_mov_b64_e32 v[40:41], v[236:237]
	v_mov_b64_e32 v[42:43], v[238:239]
	v_mov_b64_e32 v[44:45], v[240:241]
	v_mov_b64_e32 v[46:47], v[242:243]
	v_mov_b64_e32 v[48:49], v[244:245]
	v_mov_b64_e32 v[50:51], v[246:247]
	v_mov_b64_e32 v[52:53], v[248:249]
	v_mov_b64_e32 v[54:55], v[250:251]
	s_add_i32 s98, s29, 0xb0
	v_or_b32_e32 v252, s98, v1
	v_bitop3_b32 v253, s98, v166, v1 bitop3:0xc8
	v_and_or_b32 v236, v252, 63, v162
	v_cmp_gt_i32_e32 vcc, s47, v252
	v_readlane_b32 s100, v254, 22
	v_readlane_b32 s101, v254, 23
	v_cndmask_b32_e32 v252, v236, v253, vcc
	v_lshl_or_b32 v252, v252, 8, v168
	s_nop 2
	global_load_dwordx4 v[236:239], v252, s[100:101]
	global_load_dwordx4 v[240:243], v252, s[100:101] offset:16
	global_load_dwordx4 v[244:247], v252, s[100:101] offset:32
	global_load_dwordx4 v[248:251], v252, s[100:101] offset:48
	s_and_b64 vcc, exec, s[6:7]
	s_mov_b64 s[38:39], 0x1b500000
	v_mov_b32_e32 v34, v40
	v_mul_f32_e32 v40, v32, v44
	v_mul_f32_e32 v56, v24, v45
	v_mul_f32_e32 v44, v24, v44
	v_mul_f32_e32 v58, v32, v45
	v_mov_b32_e32 v24, v33
	v_mov_b32_e32 v32, v25
	v_mov_b32_e32 v60, v48
	v_mul_f32_e32 v48, v28, v52
	v_mul_f32_e32 v62, v20, v53
	v_mul_f32_e32 v52, v20, v52
	v_mul_f32_e32 v64, v28, v53
	v_mov_b32_e32 v20, v29
	v_mov_b32_e32 v28, v21
	v_mov_b32_e32 v35, v42
	v_mov_b32_e32 v42, v41
	v_mov_b32_e32 v61, v50
	v_mov_b32_e32 v50, v49
	v_pk_mul_f32 v[24:25], v[24:25], v[46:47]
	v_pk_mul_f32 v[32:33], v[32:33], v[46:47]
	v_pk_mul_f32 v[68:69], v[20:21], v[54:55]
	v_pk_mul_f32 v[54:55], v[28:29], v[54:55]
	v_pk_mul_f32 v[66:67], v[22:23], v[42:43]
	v_pk_mul_f32 v[42:43], v[30:31], v[42:43]
	v_pk_mul_f32 v[46:47], v[18:19], v[50:51]
	v_pk_mul_f32 v[50:51], v[26:27], v[50:51]
	v_mov_b32_e32 v41, v24
	v_mov_b32_e32 v57, v25
	v_mov_b32_e32 v45, v32
	v_mov_b32_e32 v59, v33
	v_mov_b32_e32 v49, v68
	v_mov_b32_e32 v63, v69
	v_mov_b32_e32 v53, v54
	v_mov_b32_e32 v65, v55
	v_pk_fma_f32 v[28:29], v[30:31], v[34:35], v[66:67] neg_lo:[0,0,1] neg_hi:[0,0,1]
	v_pk_fma_f32 v[20:21], v[22:23], v[34:35], v[42:43]
	v_pk_fma_f32 v[32:33], v[26:27], v[60:61], v[46:47] neg_lo:[0,0,1] neg_hi:[0,0,1]
	v_pk_fma_f32 v[24:25], v[18:19], v[60:61], v[50:51]
	v_pk_add_f32 v[30:31], v[40:41], v[56:57] neg_lo:[0,1] neg_hi:[0,1]
	v_pk_add_f32 v[22:23], v[44:45], v[58:59]
	v_pk_add_f32 v[34:35], v[48:49], v[62:63] neg_lo:[0,1] neg_hi:[0,1]
	v_pk_add_f32 v[26:27], v[52:53], v[64:65]
	s_cbranch_vccnz .LBB0_3193
	v_pk_mul_f32 v[30:31], v[30:31], s[26:27] op_sel_hi:[1,0]
	v_pk_mul_f32 v[28:29], v[28:29], s[26:27] op_sel_hi:[1,0]
	v_pk_mul_f32 v[22:23], v[22:23], s[26:27] op_sel_hi:[1,0]
	v_pk_mul_f32 v[20:21], v[20:21], s[26:27] op_sel_hi:[1,0]
	v_pk_mul_f32 v[34:35], v[34:35], s[26:27] op_sel_hi:[1,0]
	v_pk_mul_f32 v[32:33], v[32:33], s[26:27] op_sel_hi:[1,0]
	v_pk_mul_f32 v[26:27], v[26:27], s[26:27] op_sel_hi:[1,0]
	v_pk_mul_f32 v[24:25], v[24:25], s[26:27] op_sel_hi:[1,0]
	s_mov_b64 s[38:39], 0x19300000
